# snake MFMA order in every 16x16x32 compute segment: consecutive MFMAs always share the A or B fragment (swap 2<->3 and 6<->7 per group of 8), on keep_v8
# speedup vs baseline: 1.0004x; 1.0004x over previous
.LBB0_182:
	s_add_u32 s6, s4, 0xfffc0080
	s_addc_u32 s7, s5, -1
	s_add_i32 s9, 0, 0x10000
	s_cmp_eq_u32 s53, 12
	s_cselect_b32 s27, s39, s7
	s_cselect_b32 s26, s49, s6
	v_add_u32_e32 v0, s9, v189
	s_cselect_b32 s7, s15, s52
	s_cselect_b32 s6, s50, s51
	s_add_i32 s83, 0, 0x14000
	ds_read_b128 v[130:133], v0
	ds_read_b128 v[134:137], v0 offset:1024
	ds_read_b128 v[162:165], v0 offset:2048
	ds_read_b128 v[166:169], v0 offset:3072
	v_add_u32_e32 v0, s83, v189
	ds_read_b128 v[170:173], v0
	ds_read_b128 v[174:177], v0 offset:1024
	ds_read_b128 v[178:181], v0 offset:2048
	ds_read_b128 v[182:185], v0 offset:3072
	v_lshl_add_u64 v[148:149], s[4:5], 0, v[158:159]
	s_add_i32 m0, s40, 0xc000
	ds_read_b128 v[196:199], v193
	ds_read_b128 v[200:203], v193 offset:1024
	ds_read_b128 v[204:207], v193 offset:2048
	ds_read_b128 v[208:211], v193 offset:3072
	ds_read_b128 v[212:215], v193 offset:4096
	ds_read_b128 v[216:219], v193 offset:5120
	ds_read_b128 v[220:223], v193 offset:6144
	ds_read_b128 v[224:227], v193 offset:7168
	global_load_lds_dwordx4 v[148:149], off
	s_add_i32 m0, s40, 0xe000
	v_lshl_add_u64 v[148:149], s[4:5], 0, v[160:161]
	global_load_lds_dwordx4 v[148:149], off
	s_waitcnt vmcnt(8)
	s_waitcnt lgkmcnt(0)
	s_barrier
	s_setprio 1
	v_mfma_f32_16x16x32_bf16 v[126:129], v[130:133], v[196:199], v[126:129]
	v_mfma_f32_16x16x32_bf16 v[122:125], v[162:165], v[196:199], v[122:125]
	v_mfma_f32_16x16x32_bf16 v[114:117], v[162:165], v[204:207], v[114:117]
	v_mfma_f32_16x16x32_bf16 v[118:121], v[130:133], v[204:207], v[118:121]
	v_mfma_f32_16x16x32_bf16 v[102:105], v[130:133], v[212:215], v[102:105]
	v_mfma_f32_16x16x32_bf16 v[98:101], v[162:165], v[212:215], v[98:101]
	v_mfma_f32_16x16x32_bf16 v[82:85], v[162:165], v[220:223], v[82:85]
	v_mfma_f32_16x16x32_bf16 v[86:89], v[130:133], v[220:223], v[86:89]
	v_mfma_f32_16x16x32_bf16 v[126:129], v[134:137], v[200:203], v[126:129]
	v_mfma_f32_16x16x32_bf16 v[122:125], v[166:169], v[200:203], v[122:125]
	v_mfma_f32_16x16x32_bf16 v[114:117], v[166:169], v[208:211], v[114:117]
	v_mfma_f32_16x16x32_bf16 v[118:121], v[134:137], v[208:211], v[118:121]
	v_mfma_f32_16x16x32_bf16 v[102:105], v[134:137], v[216:219], v[102:105]
	v_mfma_f32_16x16x32_bf16 v[98:101], v[166:169], v[216:219], v[98:101]
	v_mfma_f32_16x16x32_bf16 v[82:85], v[166:169], v[224:227], v[82:85]
	v_mfma_f32_16x16x32_bf16 v[86:89], v[134:137], v[224:227], v[86:89]
	v_mfma_f32_16x16x32_bf16 v[110:113], v[170:173], v[196:199], v[110:113]
	v_mfma_f32_16x16x32_bf16 v[106:109], v[178:181], v[196:199], v[106:109]
	v_mfma_f32_16x16x32_bf16 v[90:93], v[178:181], v[204:207], v[90:93]
	v_mfma_f32_16x16x32_bf16 v[94:97], v[170:173], v[204:207], v[94:97]
	v_mfma_f32_16x16x32_bf16 v[78:81], v[170:173], v[212:215], v[78:81]
	v_mfma_f32_16x16x32_bf16 v[74:77], v[178:181], v[212:215], v[74:77]
	v_mfma_f32_16x16x32_bf16 v[66:69], v[178:181], v[220:223], v[66:69]
	v_mfma_f32_16x16x32_bf16 v[70:73], v[170:173], v[220:223], v[70:73]
	v_mfma_f32_16x16x32_bf16 v[110:113], v[174:177], v[200:203], v[110:113]
	v_mfma_f32_16x16x32_bf16 v[106:109], v[182:185], v[200:203], v[106:109]
	v_mfma_f32_16x16x32_bf16 v[90:93], v[182:185], v[208:211], v[90:93]
	v_mfma_f32_16x16x32_bf16 v[94:97], v[174:177], v[208:211], v[94:97]
	v_mfma_f32_16x16x32_bf16 v[78:81], v[174:177], v[216:219], v[78:81]
	v_mfma_f32_16x16x32_bf16 v[74:77], v[182:185], v[216:219], v[74:77]
	v_mfma_f32_16x16x32_bf16 v[66:69], v[182:185], v[224:227], v[66:69]
	v_mfma_f32_16x16x32_bf16 v[70:73], v[174:177], v[224:227], v[70:73]
	s_setprio 0
	s_barrier
	s_add_i32 s9, s9, s29
	v_lshl_add_u64 v[148:149], s[6:7], 0, v[142:143]
	s_mov_b32 m0, s9
	ds_read_b128 v[196:199], v193 offset:16384
	ds_read_b128 v[200:203], v193 offset:17408
	ds_read_b128 v[204:207], v193 offset:18432
	ds_read_b128 v[208:211], v193 offset:19456
	ds_read_b128 v[212:215], v193 offset:20480
	ds_read_b128 v[216:219], v193 offset:21504
	ds_read_b128 v[220:223], v193 offset:22528
	ds_read_b128 v[224:227], v193 offset:23552
	global_load_lds_dwordx4 v[148:149], off
	s_add_i32 m0, s9, 0x2000
	s_add_u32 s78, s6, 0x40000
	v_lshl_add_u64 v[150:151], s[6:7], 0, v[138:139]
	s_addc_u32 s79, s7, 0
	s_add_i32 s9, s83, s29
	global_load_lds_dwordx4 v[150:151], off
	v_lshl_add_u64 v[186:187], s[78:79], 0, v[142:143]
	s_mov_b32 m0, s9
	v_lshl_add_u64 v[228:229], s[26:27], 0, v[140:141]
	global_load_lds_dwordx4 v[186:187], off
	s_add_i32 m0, s9, 0x2000
	v_lshl_add_u64 v[186:187], s[78:79], 0, v[138:139]
	global_load_lds_dwordx4 v[186:187], off
	s_mov_b32 m0, s40
	v_lshl_add_u64 v[186:187], s[26:27], 0, v[144:145]
	global_load_lds_dwordx4 v[186:187], off
	s_mov_b32 m0, s41
	s_nop 0
	global_load_lds_dwordx4 v[228:229], off
	s_waitcnt vmcnt(8)
	s_waitcnt lgkmcnt(0)
	s_barrier
	s_setprio 1
	v_mfma_f32_16x16x32_bf16 v[62:65], v[130:133], v[196:199], v[62:65]
	v_mfma_f32_16x16x32_bf16 v[58:61], v[162:165], v[196:199], v[58:61]
	v_mfma_f32_16x16x32_bf16 v[50:53], v[162:165], v[204:207], v[50:53]
	v_mfma_f32_16x16x32_bf16 v[54:57], v[130:133], v[204:207], v[54:57]
	v_mfma_f32_16x16x32_bf16 v[38:41], v[130:133], v[212:215], v[38:41]
	v_mfma_f32_16x16x32_bf16 v[34:37], v[162:165], v[212:215], v[34:37]
	v_mfma_f32_16x16x32_bf16 v[18:21], v[162:165], v[220:223], v[18:21]
	v_mfma_f32_16x16x32_bf16 v[22:25], v[130:133], v[220:223], v[22:25]
	v_mfma_f32_16x16x32_bf16 v[62:65], v[134:137], v[200:203], v[62:65]
	v_mfma_f32_16x16x32_bf16 v[58:61], v[166:169], v[200:203], v[58:61]
	v_mfma_f32_16x16x32_bf16 v[50:53], v[166:169], v[208:211], v[50:53]
	v_mfma_f32_16x16x32_bf16 v[54:57], v[134:137], v[208:211], v[54:57]
	v_mfma_f32_16x16x32_bf16 v[38:41], v[134:137], v[216:219], v[38:41]
	v_mfma_f32_16x16x32_bf16 v[34:37], v[166:169], v[216:219], v[34:37]
	v_mfma_f32_16x16x32_bf16 v[18:21], v[166:169], v[224:227], v[18:21]
	v_mfma_f32_16x16x32_bf16 v[22:25], v[134:137], v[224:227], v[22:25]
	v_mfma_f32_16x16x32_bf16 v[46:49], v[170:173], v[196:199], v[46:49]
	v_mfma_f32_16x16x32_bf16 v[42:45], v[178:181], v[196:199], v[42:45]
	v_mfma_f32_16x16x32_bf16 v[26:29], v[178:181], v[204:207], v[26:29]
	v_mfma_f32_16x16x32_bf16 v[30:33], v[170:173], v[204:207], v[30:33]
	v_mfma_f32_16x16x32_bf16 v[14:17], v[170:173], v[212:215], v[14:17]
	v_mfma_f32_16x16x32_bf16 v[10:13], v[178:181], v[212:215], v[10:13]
	v_mfma_f32_16x16x32_bf16 v[2:5], v[178:181], v[220:223], v[2:5]
	v_mfma_f32_16x16x32_bf16 v[6:9], v[170:173], v[220:223], v[6:9]
	v_mfma_f32_16x16x32_bf16 v[46:49], v[174:177], v[200:203], v[46:49]
	v_mfma_f32_16x16x32_bf16 v[42:45], v[182:185], v[200:203], v[42:45]
	v_mfma_f32_16x16x32_bf16 v[26:29], v[182:185], v[208:211], v[26:29]
	v_mfma_f32_16x16x32_bf16 v[30:33], v[174:177], v[208:211], v[30:33]
	v_mfma_f32_16x16x32_bf16 v[14:17], v[174:177], v[216:219], v[14:17]
	v_mfma_f32_16x16x32_bf16 v[10:13], v[182:185], v[216:219], v[10:13]
	v_mfma_f32_16x16x32_bf16 v[2:5], v[182:185], v[224:227], v[2:5]
	v_mfma_f32_16x16x32_bf16 v[6:9], v[174:177], v[224:227], v[6:9]
	s_setprio 0
	s_barrier
	s_add_i32 s9, 0, 0x18000
	v_add_u32_e32 v0, s9, v189
	s_add_i32 s78, 0, 0x1c000
	ds_read_b128 v[130:133], v0
	ds_read_b128 v[134:137], v0 offset:1024
	ds_read_b128 v[162:165], v0 offset:2048
	ds_read_b128 v[166:169], v0 offset:3072
	v_add_u32_e32 v0, s78, v189
	ds_read_b128 v[170:173], v0
	ds_read_b128 v[174:177], v0 offset:1024
	ds_read_b128 v[178:181], v0 offset:2048
	ds_read_b128 v[182:185], v0 offset:3072
	s_add_u32 s26, s26, 0x40000
	s_addc_u32 s27, s27, 0
	s_mov_b32 m0, s42
	v_lshl_add_u64 v[230:231], s[26:27], 0, v[144:145]
	ds_read_b128 v[196:199], v193 offset:32768
	ds_read_b128 v[200:203], v193 offset:33792
	ds_read_b128 v[204:207], v193 offset:34816
	ds_read_b128 v[208:211], v193 offset:35840
	ds_read_b128 v[212:215], v193 offset:36864
	ds_read_b128 v[216:219], v193 offset:37888
	ds_read_b128 v[220:223], v193 offset:38912
	ds_read_b128 v[224:227], v193 offset:39936
	global_load_lds_dwordx4 v[230:231], off
	s_mov_b32 m0, s43
	v_lshl_add_u64 v[230:231], s[26:27], 0, v[140:141]
	global_load_lds_dwordx4 v[230:231], off
	s_waitcnt vmcnt(8)
	s_waitcnt lgkmcnt(0)
	s_barrier
	s_setprio 1
	v_mfma_f32_16x16x32_bf16 v[126:129], v[130:133], v[196:199], v[126:129]
	v_mfma_f32_16x16x32_bf16 v[122:125], v[162:165], v[196:199], v[122:125]
	v_mfma_f32_16x16x32_bf16 v[114:117], v[162:165], v[204:207], v[114:117]
	v_mfma_f32_16x16x32_bf16 v[118:121], v[130:133], v[204:207], v[118:121]
	v_mfma_f32_16x16x32_bf16 v[102:105], v[130:133], v[212:215], v[102:105]
	v_mfma_f32_16x16x32_bf16 v[98:101], v[162:165], v[212:215], v[98:101]
	v_mfma_f32_16x16x32_bf16 v[82:85], v[162:165], v[220:223], v[82:85]
	v_mfma_f32_16x16x32_bf16 v[86:89], v[130:133], v[220:223], v[86:89]
	v_mfma_f32_16x16x32_bf16 v[126:129], v[134:137], v[200:203], v[126:129]
	v_mfma_f32_16x16x32_bf16 v[122:125], v[166:169], v[200:203], v[122:125]
	v_mfma_f32_16x16x32_bf16 v[114:117], v[166:169], v[208:211], v[114:117]
	v_mfma_f32_16x16x32_bf16 v[118:121], v[134:137], v[208:211], v[118:121]
	v_mfma_f32_16x16x32_bf16 v[102:105], v[134:137], v[216:219], v[102:105]
	v_mfma_f32_16x16x32_bf16 v[98:101], v[166:169], v[216:219], v[98:101]
	v_mfma_f32_16x16x32_bf16 v[82:85], v[166:169], v[224:227], v[82:85]
	v_mfma_f32_16x16x32_bf16 v[86:89], v[134:137], v[224:227], v[86:89]
	v_mfma_f32_16x16x32_bf16 v[110:113], v[170:173], v[196:199], v[110:113]
	v_mfma_f32_16x16x32_bf16 v[106:109], v[178:181], v[196:199], v[106:109]
	v_mfma_f32_16x16x32_bf16 v[90:93], v[178:181], v[204:207], v[90:93]
	v_mfma_f32_16x16x32_bf16 v[94:97], v[170:173], v[204:207], v[94:97]
	v_mfma_f32_16x16x32_bf16 v[78:81], v[170:173], v[212:215], v[78:81]
	v_mfma_f32_16x16x32_bf16 v[74:77], v[178:181], v[212:215], v[74:77]
	v_mfma_f32_16x16x32_bf16 v[66:69], v[178:181], v[220:223], v[66:69]
	v_mfma_f32_16x16x32_bf16 v[70:73], v[170:173], v[220:223], v[70:73]
	v_mfma_f32_16x16x32_bf16 v[110:113], v[174:177], v[200:203], v[110:113]
	v_mfma_f32_16x16x32_bf16 v[106:109], v[182:185], v[200:203], v[106:109]
	v_mfma_f32_16x16x32_bf16 v[90:93], v[182:185], v[208:211], v[90:93]
	v_mfma_f32_16x16x32_bf16 v[94:97], v[174:177], v[208:211], v[94:97]
	v_mfma_f32_16x16x32_bf16 v[78:81], v[174:177], v[216:219], v[78:81]
	v_mfma_f32_16x16x32_bf16 v[74:77], v[182:185], v[216:219], v[74:77]
	v_mfma_f32_16x16x32_bf16 v[66:69], v[182:185], v[224:227], v[66:69]
	v_mfma_f32_16x16x32_bf16 v[70:73], v[174:177], v[224:227], v[70:73]
	s_setprio 0
	s_barrier
	s_add_i32 s9, s9, s29
	v_lshl_add_u64 v[148:149], v[148:149], 0, s[70:71]
	s_mov_b32 m0, s9
	ds_read_b128 v[196:199], v193 offset:49152
	ds_read_b128 v[200:203], v193 offset:50176
	ds_read_b128 v[204:207], v193 offset:51200
	ds_read_b128 v[208:211], v193 offset:52224
	ds_read_b128 v[212:215], v193 offset:53248
	ds_read_b128 v[216:219], v193 offset:54272
	ds_read_b128 v[220:223], v193 offset:55296
	ds_read_b128 v[224:227], v193 offset:56320
	global_load_lds_dwordx4 v[148:149], off
	s_add_i32 m0, s9, 0x2000
	s_add_u32 s6, s6, 0x40080
	v_lshl_add_u64 v[148:149], v[150:151], 0, s[70:71]
	s_addc_u32 s7, s7, 0
	s_add_i32 s9, s78, s29
	global_load_lds_dwordx4 v[148:149], off
	s_mov_b32 m0, s9
	v_lshl_add_u64 v[148:149], s[6:7], 0, v[142:143]
	global_load_lds_dwordx4 v[148:149], off
	s_add_i32 m0, s9, 0x2000
	v_lshl_add_u64 v[148:149], s[6:7], 0, v[138:139]
	global_load_lds_dwordx4 v[148:149], off
	s_mov_b32 m0, s44
	v_lshl_add_u64 v[148:149], v[186:187], 0, s[70:71]
	global_load_lds_dwordx4 v[148:149], off
	s_mov_b32 m0, s45
	v_lshl_add_u64 v[148:149], v[228:229], 0, s[70:71]
	global_load_lds_dwordx4 v[148:149], off
	s_waitcnt vmcnt(8)
	s_waitcnt lgkmcnt(0)
	s_barrier
	s_setprio 1
	v_mfma_f32_16x16x32_bf16 v[62:65], v[130:133], v[196:199], v[62:65]
	v_mfma_f32_16x16x32_bf16 v[58:61], v[162:165], v[196:199], v[58:61]
	v_mfma_f32_16x16x32_bf16 v[50:53], v[162:165], v[204:207], v[50:53]
	v_mfma_f32_16x16x32_bf16 v[54:57], v[130:133], v[204:207], v[54:57]
	v_mfma_f32_16x16x32_bf16 v[38:41], v[130:133], v[212:215], v[38:41]
	v_mfma_f32_16x16x32_bf16 v[34:37], v[162:165], v[212:215], v[34:37]
	v_mfma_f32_16x16x32_bf16 v[18:21], v[162:165], v[220:223], v[18:21]
	v_mfma_f32_16x16x32_bf16 v[22:25], v[130:133], v[220:223], v[22:25]
	v_mfma_f32_16x16x32_bf16 v[62:65], v[134:137], v[200:203], v[62:65]
	v_mfma_f32_16x16x32_bf16 v[58:61], v[166:169], v[200:203], v[58:61]
	v_mfma_f32_16x16x32_bf16 v[50:53], v[166:169], v[208:211], v[50:53]
	v_mfma_f32_16x16x32_bf16 v[54:57], v[134:137], v[208:211], v[54:57]
	v_mfma_f32_16x16x32_bf16 v[38:41], v[134:137], v[216:219], v[38:41]
	v_mfma_f32_16x16x32_bf16 v[34:37], v[166:169], v[216:219], v[34:37]
	v_mfma_f32_16x16x32_bf16 v[18:21], v[166:169], v[224:227], v[18:21]
	v_mfma_f32_16x16x32_bf16 v[22:25], v[134:137], v[224:227], v[22:25]
	v_mfma_f32_16x16x32_bf16 v[46:49], v[170:173], v[196:199], v[46:49]
	v_mfma_f32_16x16x32_bf16 v[42:45], v[178:181], v[196:199], v[42:45]
	v_mfma_f32_16x16x32_bf16 v[26:29], v[178:181], v[204:207], v[26:29]
	v_mfma_f32_16x16x32_bf16 v[30:33], v[170:173], v[204:207], v[30:33]
	v_mfma_f32_16x16x32_bf16 v[14:17], v[170:173], v[212:215], v[14:17]
	v_mfma_f32_16x16x32_bf16 v[10:13], v[178:181], v[212:215], v[10:13]
	v_mfma_f32_16x16x32_bf16 v[2:5], v[178:181], v[220:223], v[2:5]
	v_mfma_f32_16x16x32_bf16 v[6:9], v[170:173], v[220:223], v[6:9]
	v_mfma_f32_16x16x32_bf16 v[46:49], v[174:177], v[200:203], v[46:49]
	v_mfma_f32_16x16x32_bf16 v[42:45], v[182:185], v[200:203], v[42:45]
	v_mfma_f32_16x16x32_bf16 v[26:29], v[182:185], v[208:211], v[26:29]
	v_mfma_f32_16x16x32_bf16 v[30:33], v[174:177], v[208:211], v[30:33]
	v_mfma_f32_16x16x32_bf16 v[14:17], v[174:177], v[216:219], v[14:17]
	v_mfma_f32_16x16x32_bf16 v[10:13], v[182:185], v[216:219], v[10:13]
	v_mfma_f32_16x16x32_bf16 v[2:5], v[182:185], v[224:227], v[2:5]
	v_mfma_f32_16x16x32_bf16 v[6:9], v[174:177], v[224:227], v[6:9]
	s_setprio 0
	s_barrier
	s_add_i32 s53, s53, 2
	s_add_u32 s4, s4, 0x100
	s_addc_u32 s5, s5, 0
	s_add_u32 s51, s51, 0x100
	s_addc_u32 s52, s52, 0
	s_cmp_gt_u32 s53, 13
	s_cbranch_scc0 .LBB0_182
	s_and_b64 vcc, exec, s[36:37]
	s_cbranch_vccz .LBB0_185
	s_barrier

.LBB0_220:
	s_add_u32 s9, s36, 0xfffc0080
	s_addc_u32 s26, s37, -1
	s_add_i32 s60, 0, 0x10000
	s_cmp_eq_u32 s53, 12
	s_cselect_b32 s39, s19, s26
	s_cselect_b32 s38, s49, s9
	v_add_u32_e32 v148, s60, v141
	s_cselect_b32 s27, s17, s52
	s_cselect_b32 s26, s50, s51
	s_add_i32 s9, 0, 0x14000
	ds_read_b128 v[144:147], v148
	ds_read_b128 v[156:159], v148 offset:1024
	ds_read_b128 v[160:163], v148 offset:2048
	ds_read_b128 v[164:167], v148 offset:3072
	v_add_u32_e32 v148, s9, v141
	ds_read_b128 v[168:171], v148
	ds_read_b128 v[172:175], v148 offset:1024
	ds_read_b128 v[176:179], v148 offset:2048
	ds_read_b128 v[180:183], v148 offset:3072
	v_lshl_add_u64 v[148:149], s[36:37], 0, v[136:137]
	s_add_i32 m0, s40, 0xc000
	ds_read_b128 v[184:187], v143
	ds_read_b128 v[188:191], v143 offset:1024
	ds_read_b128 v[192:195], v143 offset:2048
	ds_read_b128 v[196:199], v143 offset:3072
	ds_read_b128 v[200:203], v143 offset:4096
	ds_read_b128 v[204:207], v143 offset:5120
	ds_read_b128 v[208:211], v143 offset:6144
	ds_read_b128 v[212:215], v143 offset:7168
	global_load_lds_dwordx4 v[148:149], off
	s_add_i32 m0, s40, 0xe000
	v_lshl_add_u64 v[148:149], s[36:37], 0, v[138:139]
	global_load_lds_dwordx4 v[148:149], off
	s_waitcnt vmcnt(8)
	s_waitcnt lgkmcnt(0)
	s_barrier
	s_setprio 1
	v_mfma_f32_16x16x32_bf16 v[126:129], v[144:147], v[184:187], v[126:129]
	v_mfma_f32_16x16x32_bf16 v[122:125], v[160:163], v[184:187], v[122:125]
	v_mfma_f32_16x16x32_bf16 v[114:117], v[160:163], v[192:195], v[114:117]
	v_mfma_f32_16x16x32_bf16 v[118:121], v[144:147], v[192:195], v[118:121]
	v_mfma_f32_16x16x32_bf16 v[102:105], v[144:147], v[200:203], v[102:105]
	v_mfma_f32_16x16x32_bf16 v[98:101], v[160:163], v[200:203], v[98:101]
	v_mfma_f32_16x16x32_bf16 v[82:85], v[160:163], v[208:211], v[82:85]
	v_mfma_f32_16x16x32_bf16 v[86:89], v[144:147], v[208:211], v[86:89]
	v_mfma_f32_16x16x32_bf16 v[126:129], v[156:159], v[188:191], v[126:129]
	v_mfma_f32_16x16x32_bf16 v[122:125], v[164:167], v[188:191], v[122:125]
	v_mfma_f32_16x16x32_bf16 v[114:117], v[164:167], v[196:199], v[114:117]
	v_mfma_f32_16x16x32_bf16 v[118:121], v[156:159], v[196:199], v[118:121]
	v_mfma_f32_16x16x32_bf16 v[102:105], v[156:159], v[204:207], v[102:105]
	v_mfma_f32_16x16x32_bf16 v[98:101], v[164:167], v[204:207], v[98:101]
	v_mfma_f32_16x16x32_bf16 v[82:85], v[164:167], v[212:215], v[82:85]
	v_mfma_f32_16x16x32_bf16 v[86:89], v[156:159], v[212:215], v[86:89]
	v_mfma_f32_16x16x32_bf16 v[110:113], v[168:171], v[184:187], v[110:113]
	v_mfma_f32_16x16x32_bf16 v[106:109], v[176:179], v[184:187], v[106:109]
	v_mfma_f32_16x16x32_bf16 v[90:93], v[176:179], v[192:195], v[90:93]
	v_mfma_f32_16x16x32_bf16 v[94:97], v[168:171], v[192:195], v[94:97]
	v_mfma_f32_16x16x32_bf16 v[78:81], v[168:171], v[200:203], v[78:81]
	v_mfma_f32_16x16x32_bf16 v[74:77], v[176:179], v[200:203], v[74:77]
	v_mfma_f32_16x16x32_bf16 v[66:69], v[176:179], v[208:211], v[66:69]
	v_mfma_f32_16x16x32_bf16 v[70:73], v[168:171], v[208:211], v[70:73]
	v_mfma_f32_16x16x32_bf16 v[110:113], v[172:175], v[188:191], v[110:113]
	v_mfma_f32_16x16x32_bf16 v[106:109], v[180:183], v[188:191], v[106:109]
	v_mfma_f32_16x16x32_bf16 v[90:93], v[180:183], v[196:199], v[90:93]
	v_mfma_f32_16x16x32_bf16 v[94:97], v[172:175], v[196:199], v[94:97]
	v_mfma_f32_16x16x32_bf16 v[78:81], v[172:175], v[204:207], v[78:81]
	v_mfma_f32_16x16x32_bf16 v[74:77], v[180:183], v[204:207], v[74:77]
	v_mfma_f32_16x16x32_bf16 v[66:69], v[180:183], v[212:215], v[66:69]
	v_mfma_f32_16x16x32_bf16 v[70:73], v[172:175], v[212:215], v[70:73]
	s_setprio 0
	s_barrier
	s_add_i32 s60, s60, s29
	v_lshl_add_u64 v[148:149], s[26:27], 0, v[0:1]
	s_mov_b32 m0, s60
	ds_read_b128 v[184:187], v143 offset:16384
	ds_read_b128 v[188:191], v143 offset:17408
	ds_read_b128 v[192:195], v143 offset:18432
	ds_read_b128 v[196:199], v143 offset:19456
	ds_read_b128 v[200:203], v143 offset:20480
	ds_read_b128 v[204:207], v143 offset:21504
	ds_read_b128 v[208:211], v143 offset:22528
	ds_read_b128 v[212:215], v143 offset:23552
	global_load_lds_dwordx4 v[148:149], off
	s_add_i32 m0, s60, 0x2000
	s_add_u32 s60, s26, 0x40000
	v_lshl_add_u64 v[150:151], s[26:27], 0, v[130:131]
	s_addc_u32 s61, s27, 0
	s_add_i32 s9, s9, s29
	global_load_lds_dwordx4 v[150:151], off
	v_lshl_add_u64 v[216:217], s[60:61], 0, v[0:1]
	s_mov_b32 m0, s9
	v_lshl_add_u64 v[218:219], s[38:39], 0, v[132:133]
	global_load_lds_dwordx4 v[216:217], off
	s_add_i32 m0, s9, 0x2000
	v_lshl_add_u64 v[216:217], s[60:61], 0, v[130:131]
	global_load_lds_dwordx4 v[216:217], off
	s_mov_b32 m0, s40
	v_lshl_add_u64 v[216:217], s[38:39], 0, v[134:135]
	global_load_lds_dwordx4 v[216:217], off
	s_mov_b32 m0, s41
	s_nop 0
	global_load_lds_dwordx4 v[218:219], off
	s_waitcnt vmcnt(8)
	s_waitcnt lgkmcnt(0)
	s_barrier
	s_setprio 1
	v_mfma_f32_16x16x32_bf16 v[62:65], v[144:147], v[184:187], v[62:65]
	v_mfma_f32_16x16x32_bf16 v[58:61], v[160:163], v[184:187], v[58:61]
	v_mfma_f32_16x16x32_bf16 v[50:53], v[160:163], v[192:195], v[50:53]
	v_mfma_f32_16x16x32_bf16 v[54:57], v[144:147], v[192:195], v[54:57]
	v_mfma_f32_16x16x32_bf16 v[38:41], v[144:147], v[200:203], v[38:41]
	v_mfma_f32_16x16x32_bf16 v[34:37], v[160:163], v[200:203], v[34:37]
	v_mfma_f32_16x16x32_bf16 v[18:21], v[160:163], v[208:211], v[18:21]
	v_mfma_f32_16x16x32_bf16 v[22:25], v[144:147], v[208:211], v[22:25]
	v_mfma_f32_16x16x32_bf16 v[62:65], v[156:159], v[188:191], v[62:65]
	v_mfma_f32_16x16x32_bf16 v[58:61], v[164:167], v[188:191], v[58:61]
	v_mfma_f32_16x16x32_bf16 v[50:53], v[164:167], v[196:199], v[50:53]
	v_mfma_f32_16x16x32_bf16 v[54:57], v[156:159], v[196:199], v[54:57]
	v_mfma_f32_16x16x32_bf16 v[38:41], v[156:159], v[204:207], v[38:41]
	v_mfma_f32_16x16x32_bf16 v[34:37], v[164:167], v[204:207], v[34:37]
	v_mfma_f32_16x16x32_bf16 v[18:21], v[164:167], v[212:215], v[18:21]
	v_mfma_f32_16x16x32_bf16 v[22:25], v[156:159], v[212:215], v[22:25]
	v_mfma_f32_16x16x32_bf16 v[46:49], v[168:171], v[184:187], v[46:49]
	v_mfma_f32_16x16x32_bf16 v[42:45], v[176:179], v[184:187], v[42:45]
	v_mfma_f32_16x16x32_bf16 v[26:29], v[176:179], v[192:195], v[26:29]
	v_mfma_f32_16x16x32_bf16 v[30:33], v[168:171], v[192:195], v[30:33]
	v_mfma_f32_16x16x32_bf16 v[14:17], v[168:171], v[200:203], v[14:17]
	v_mfma_f32_16x16x32_bf16 v[10:13], v[176:179], v[200:203], v[10:13]
	v_mfma_f32_16x16x32_bf16 v[2:5], v[176:179], v[208:211], v[2:5]
	v_mfma_f32_16x16x32_bf16 v[6:9], v[168:171], v[208:211], v[6:9]
	v_mfma_f32_16x16x32_bf16 v[46:49], v[172:175], v[188:191], v[46:49]
	v_mfma_f32_16x16x32_bf16 v[42:45], v[180:183], v[188:191], v[42:45]
	v_mfma_f32_16x16x32_bf16 v[26:29], v[180:183], v[196:199], v[26:29]
	v_mfma_f32_16x16x32_bf16 v[30:33], v[172:175], v[196:199], v[30:33]
	v_mfma_f32_16x16x32_bf16 v[14:17], v[172:175], v[204:207], v[14:17]
	v_mfma_f32_16x16x32_bf16 v[10:13], v[180:183], v[204:207], v[10:13]
	v_mfma_f32_16x16x32_bf16 v[2:5], v[180:183], v[212:215], v[2:5]
	v_mfma_f32_16x16x32_bf16 v[6:9], v[172:175], v[212:215], v[6:9]
	s_setprio 0
	s_barrier
	s_add_i32 s9, 0, 0x18000
	s_add_i32 s60, 0, 0x1c000
	v_add_u32_e32 v164, s9, v141
	v_add_u32_e32 v180, s60, v141
	ds_read_b128 v[144:147], v164
	ds_read_b128 v[156:159], v164 offset:1024
	ds_read_b128 v[160:163], v164 offset:2048
	ds_read_b128 v[164:167], v164 offset:3072
	ds_read_b128 v[168:171], v180
	ds_read_b128 v[172:175], v180 offset:1024
	ds_read_b128 v[176:179], v180 offset:2048
	ds_read_b128 v[180:183], v180 offset:3072
	s_add_u32 s38, s38, 0x40000
	s_addc_u32 s39, s39, 0
	s_mov_b32 m0, s42
	v_lshl_add_u64 v[220:221], s[38:39], 0, v[134:135]
	ds_read_b128 v[184:187], v143 offset:32768
	ds_read_b128 v[188:191], v143 offset:33792
	ds_read_b128 v[192:195], v143 offset:34816
	ds_read_b128 v[196:199], v143 offset:35840
	ds_read_b128 v[200:203], v143 offset:36864
	ds_read_b128 v[204:207], v143 offset:37888
	ds_read_b128 v[208:211], v143 offset:38912
	ds_read_b128 v[212:215], v143 offset:39936
	global_load_lds_dwordx4 v[220:221], off
	s_mov_b32 m0, s43
	v_lshl_add_u64 v[220:221], s[38:39], 0, v[132:133]
	global_load_lds_dwordx4 v[220:221], off
	s_waitcnt vmcnt(8)
	s_waitcnt lgkmcnt(0)
	s_barrier
	s_setprio 1
	v_mfma_f32_16x16x32_bf16 v[126:129], v[144:147], v[184:187], v[126:129]
	v_mfma_f32_16x16x32_bf16 v[122:125], v[160:163], v[184:187], v[122:125]
	v_mfma_f32_16x16x32_bf16 v[114:117], v[160:163], v[192:195], v[114:117]
	v_mfma_f32_16x16x32_bf16 v[118:121], v[144:147], v[192:195], v[118:121]
	v_mfma_f32_16x16x32_bf16 v[102:105], v[144:147], v[200:203], v[102:105]
	v_mfma_f32_16x16x32_bf16 v[98:101], v[160:163], v[200:203], v[98:101]
	v_mfma_f32_16x16x32_bf16 v[82:85], v[160:163], v[208:211], v[82:85]
	v_mfma_f32_16x16x32_bf16 v[86:89], v[144:147], v[208:211], v[86:89]
	v_mfma_f32_16x16x32_bf16 v[126:129], v[156:159], v[188:191], v[126:129]
	v_mfma_f32_16x16x32_bf16 v[122:125], v[164:167], v[188:191], v[122:125]
	v_mfma_f32_16x16x32_bf16 v[114:117], v[164:167], v[196:199], v[114:117]
	v_mfma_f32_16x16x32_bf16 v[118:121], v[156:159], v[196:199], v[118:121]
	v_mfma_f32_16x16x32_bf16 v[102:105], v[156:159], v[204:207], v[102:105]
	v_mfma_f32_16x16x32_bf16 v[98:101], v[164:167], v[204:207], v[98:101]
	v_mfma_f32_16x16x32_bf16 v[82:85], v[164:167], v[212:215], v[82:85]
	v_mfma_f32_16x16x32_bf16 v[86:89], v[156:159], v[212:215], v[86:89]
	v_mfma_f32_16x16x32_bf16 v[110:113], v[168:171], v[184:187], v[110:113]
	v_mfma_f32_16x16x32_bf16 v[106:109], v[176:179], v[184:187], v[106:109]
	v_mfma_f32_16x16x32_bf16 v[90:93], v[176:179], v[192:195], v[90:93]
	v_mfma_f32_16x16x32_bf16 v[94:97], v[168:171], v[192:195], v[94:97]
	v_mfma_f32_16x16x32_bf16 v[78:81], v[168:171], v[200:203], v[78:81]
	v_mfma_f32_16x16x32_bf16 v[74:77], v[176:179], v[200:203], v[74:77]
	v_mfma_f32_16x16x32_bf16 v[66:69], v[176:179], v[208:211], v[66:69]
	v_mfma_f32_16x16x32_bf16 v[70:73], v[168:171], v[208:211], v[70:73]
	v_mfma_f32_16x16x32_bf16 v[110:113], v[172:175], v[188:191], v[110:113]
	v_mfma_f32_16x16x32_bf16 v[106:109], v[180:183], v[188:191], v[106:109]
	v_mfma_f32_16x16x32_bf16 v[90:93], v[180:183], v[196:199], v[90:93]
	v_mfma_f32_16x16x32_bf16 v[94:97], v[172:175], v[196:199], v[94:97]
	v_mfma_f32_16x16x32_bf16 v[78:81], v[172:175], v[204:207], v[78:81]
	v_mfma_f32_16x16x32_bf16 v[74:77], v[180:183], v[204:207], v[74:77]
	v_mfma_f32_16x16x32_bf16 v[66:69], v[180:183], v[212:215], v[66:69]
	v_mfma_f32_16x16x32_bf16 v[70:73], v[172:175], v[212:215], v[70:73]
	s_setprio 0
	s_barrier
	s_add_i32 s9, s9, s29
	v_lshl_add_u64 v[148:149], v[148:149], 0, s[70:71]
	s_mov_b32 m0, s9
	ds_read_b128 v[184:187], v143 offset:49152
	ds_read_b128 v[188:191], v143 offset:50176
	ds_read_b128 v[192:195], v143 offset:51200
	ds_read_b128 v[196:199], v143 offset:52224
	ds_read_b128 v[200:203], v143 offset:53248
	ds_read_b128 v[204:207], v143 offset:54272
	ds_read_b128 v[208:211], v143 offset:55296
	ds_read_b128 v[212:215], v143 offset:56320
	global_load_lds_dwordx4 v[148:149], off
	s_add_i32 m0, s9, 0x2000
	s_add_u32 s26, s26, 0x40080
	v_lshl_add_u64 v[148:149], v[150:151], 0, s[70:71]
	s_addc_u32 s27, s27, 0
	s_add_i32 s9, s60, s29
	global_load_lds_dwordx4 v[148:149], off
	s_mov_b32 m0, s9
	v_lshl_add_u64 v[148:149], s[26:27], 0, v[0:1]
	global_load_lds_dwordx4 v[148:149], off
	s_add_i32 m0, s9, 0x2000
	v_lshl_add_u64 v[148:149], s[26:27], 0, v[130:131]
	global_load_lds_dwordx4 v[148:149], off
	s_mov_b32 m0, s44
	v_lshl_add_u64 v[148:149], v[216:217], 0, s[70:71]
	global_load_lds_dwordx4 v[148:149], off
	s_mov_b32 m0, s45
	v_lshl_add_u64 v[148:149], v[218:219], 0, s[70:71]
	global_load_lds_dwordx4 v[148:149], off
	s_waitcnt vmcnt(8)
	s_waitcnt lgkmcnt(0)
	s_barrier
	s_setprio 1
	v_mfma_f32_16x16x32_bf16 v[62:65], v[144:147], v[184:187], v[62:65]
	v_mfma_f32_16x16x32_bf16 v[58:61], v[160:163], v[184:187], v[58:61]
	v_mfma_f32_16x16x32_bf16 v[50:53], v[160:163], v[192:195], v[50:53]
	v_mfma_f32_16x16x32_bf16 v[54:57], v[144:147], v[192:195], v[54:57]
	v_mfma_f32_16x16x32_bf16 v[38:41], v[144:147], v[200:203], v[38:41]
	v_mfma_f32_16x16x32_bf16 v[34:37], v[160:163], v[200:203], v[34:37]
	v_mfma_f32_16x16x32_bf16 v[18:21], v[160:163], v[208:211], v[18:21]
	v_mfma_f32_16x16x32_bf16 v[22:25], v[144:147], v[208:211], v[22:25]
	v_mfma_f32_16x16x32_bf16 v[62:65], v[156:159], v[188:191], v[62:65]
	v_mfma_f32_16x16x32_bf16 v[58:61], v[164:167], v[188:191], v[58:61]
	v_mfma_f32_16x16x32_bf16 v[50:53], v[164:167], v[196:199], v[50:53]
	v_mfma_f32_16x16x32_bf16 v[54:57], v[156:159], v[196:199], v[54:57]
	v_mfma_f32_16x16x32_bf16 v[38:41], v[156:159], v[204:207], v[38:41]
	v_mfma_f32_16x16x32_bf16 v[34:37], v[164:167], v[204:207], v[34:37]
	v_mfma_f32_16x16x32_bf16 v[18:21], v[164:167], v[212:215], v[18:21]
	v_mfma_f32_16x16x32_bf16 v[22:25], v[156:159], v[212:215], v[22:25]
	v_mfma_f32_16x16x32_bf16 v[46:49], v[168:171], v[184:187], v[46:49]
	v_mfma_f32_16x16x32_bf16 v[42:45], v[176:179], v[184:187], v[42:45]
	v_mfma_f32_16x16x32_bf16 v[26:29], v[176:179], v[192:195], v[26:29]
	v_mfma_f32_16x16x32_bf16 v[30:33], v[168:171], v[192:195], v[30:33]
	v_mfma_f32_16x16x32_bf16 v[14:17], v[168:171], v[200:203], v[14:17]
	v_mfma_f32_16x16x32_bf16 v[10:13], v[176:179], v[200:203], v[10:13]
	v_mfma_f32_16x16x32_bf16 v[2:5], v[176:179], v[208:211], v[2:5]
	v_mfma_f32_16x16x32_bf16 v[6:9], v[168:171], v[208:211], v[6:9]
	v_mfma_f32_16x16x32_bf16 v[46:49], v[172:175], v[188:191], v[46:49]
	v_mfma_f32_16x16x32_bf16 v[42:45], v[180:183], v[188:191], v[42:45]
	v_mfma_f32_16x16x32_bf16 v[26:29], v[180:183], v[196:199], v[26:29]
	v_mfma_f32_16x16x32_bf16 v[30:33], v[172:175], v[196:199], v[30:33]
	v_mfma_f32_16x16x32_bf16 v[14:17], v[172:175], v[204:207], v[14:17]
	v_mfma_f32_16x16x32_bf16 v[10:13], v[180:183], v[204:207], v[10:13]
	v_mfma_f32_16x16x32_bf16 v[2:5], v[180:183], v[212:215], v[2:5]
	v_mfma_f32_16x16x32_bf16 v[6:9], v[172:175], v[212:215], v[6:9]
	s_setprio 0
	s_barrier
	s_add_i32 s53, s53, 2
	s_add_u32 s36, s36, 0x100
	s_addc_u32 s37, s37, 0
	s_add_u32 s51, s51, 0x100
	s_addc_u32 s52, s52, 0
	s_cmp_gt_u32 s53, 13
	s_cbranch_scc0 .LBB0_220
	s_and_b64 vcc, exec, s[14:15]
	s_cbranch_vccz .LBB0_223
	s_barrier

.LBB0_376:
	s_add_u32 s53, s18, s9
	s_addc_u32 s74, s19, 0
	s_add_u32 s60, s53, 0x100
	s_addc_u32 s61, s74, 0
	s_and_b64 s[26:27], s[38:39], exec
	s_cselect_b32 s61, s25, s61
	s_cselect_b32 s60, s24, s60
	s_add_u32 s9, s16, s9
	s_addc_u32 s26, s17, 0
	s_add_u32 s9, s9, 0x100
	s_addc_u32 s72, s26, 0
	s_add_i32 s92, 0, 0x10000
	s_and_b64 s[26:27], s[38:39], exec
	s_cselect_b32 s73, s23, s72
	s_cselect_b32 s72, s52, s9
	s_add_i32 s39, 0, 0x14000
	s_add_u32 vcc_lo, s53, 0x58080
	s_addc_u32 vcc_hi, s74, 0
	s_add_i32 s78, s92, s41
	s_add_i32 m0, s42, 0xc000
	s_add_i32 s93, s42, 0xe000
	s_add_i32 s91, s78, 0x2000
	v_add_u32_e32 v148, s92, v137
	s_add_u32 s74, s72, 0x10000
	ds_read_b128 v[140:143], v148
	ds_read_b128 v[144:147], v148 offset:1024
	ds_read_b128 v[156:159], v148 offset:2048
	ds_read_b128 v[160:163], v148 offset:3072
	v_add_u32_e32 v148, s39, v137
	s_addc_u32 s75, s73, 0
	s_add_i32 s79, s39, s41
	ds_read_b128 v[164:167], v148
	ds_read_b128 v[168:171], v148 offset:1024
	ds_read_b128 v[172:175], v148 offset:2048
	ds_read_b128 v[176:179], v148 offset:3072
	s_add_i32 s90, s79, 0x2000
	s_add_i32 s97, 0, 0x18000
	s_add_i32 s83, 0, 0x1c000
	s_add_u32 s26, s60, 0x58000
	s_addc_u32 s27, s61, 0
	s_add_i32 s53, s97, s41
	s_add_i32 s9, s53, 0x2000
	s_add_u32 s38, s72, 0x10080
	s_addc_u32 s39, s73, 0
	s_add_i32 s96, s83, s41
	s_add_i32 s92, s96, 0x2000
	v_lshl_add_u64 v[148:149], vcc, 0, v[134:135]
	ds_read_b128 v[180:183], v139
	ds_read_b128 v[184:187], v139 offset:1024
	ds_read_b128 v[188:191], v139 offset:2048
	ds_read_b128 v[192:195], v139 offset:3072
	ds_read_b128 v[196:199], v139 offset:4096
	ds_read_b128 v[200:203], v139 offset:5120
	ds_read_b128 v[204:207], v139 offset:6144
	ds_read_b128 v[208:211], v139 offset:7168
	global_load_lds_dwordx4 v[148:149], off
	s_mov_b32 m0, s93
	v_lshl_add_u64 v[148:149], vcc, 0, v[132:133]
	global_load_lds_dwordx4 v[148:149], off
	s_waitcnt vmcnt(8)
	s_waitcnt lgkmcnt(0)
	s_barrier
	s_setprio 1
	v_mfma_f32_16x16x32_bf16 v[126:129], v[140:143], v[180:183], v[126:129]
	v_mfma_f32_16x16x32_bf16 v[122:125], v[156:159], v[180:183], v[122:125]
	v_mfma_f32_16x16x32_bf16 v[114:117], v[156:159], v[188:191], v[114:117]
	v_mfma_f32_16x16x32_bf16 v[118:121], v[140:143], v[188:191], v[118:121]
	v_mfma_f32_16x16x32_bf16 v[102:105], v[140:143], v[196:199], v[102:105]
	v_mfma_f32_16x16x32_bf16 v[98:101], v[156:159], v[196:199], v[98:101]
	v_mfma_f32_16x16x32_bf16 v[82:85], v[156:159], v[204:207], v[82:85]
	v_mfma_f32_16x16x32_bf16 v[86:89], v[140:143], v[204:207], v[86:89]
	v_mfma_f32_16x16x32_bf16 v[126:129], v[144:147], v[184:187], v[126:129]
	v_mfma_f32_16x16x32_bf16 v[122:125], v[160:163], v[184:187], v[122:125]
	v_mfma_f32_16x16x32_bf16 v[114:117], v[160:163], v[192:195], v[114:117]
	v_mfma_f32_16x16x32_bf16 v[118:121], v[144:147], v[192:195], v[118:121]
	v_mfma_f32_16x16x32_bf16 v[102:105], v[144:147], v[200:203], v[102:105]
	v_mfma_f32_16x16x32_bf16 v[98:101], v[160:163], v[200:203], v[98:101]
	v_mfma_f32_16x16x32_bf16 v[82:85], v[160:163], v[208:211], v[82:85]
	v_mfma_f32_16x16x32_bf16 v[86:89], v[144:147], v[208:211], v[86:89]
	v_mfma_f32_16x16x32_bf16 v[110:113], v[164:167], v[180:183], v[110:113]
	v_mfma_f32_16x16x32_bf16 v[106:109], v[172:175], v[180:183], v[106:109]
	v_mfma_f32_16x16x32_bf16 v[90:93], v[172:175], v[188:191], v[90:93]
	v_mfma_f32_16x16x32_bf16 v[94:97], v[164:167], v[188:191], v[94:97]
	v_mfma_f32_16x16x32_bf16 v[78:81], v[164:167], v[196:199], v[78:81]
	v_mfma_f32_16x16x32_bf16 v[74:77], v[172:175], v[196:199], v[74:77]
	v_mfma_f32_16x16x32_bf16 v[66:69], v[172:175], v[204:207], v[66:69]
	v_mfma_f32_16x16x32_bf16 v[70:73], v[164:167], v[204:207], v[70:73]
	v_mfma_f32_16x16x32_bf16 v[110:113], v[168:171], v[184:187], v[110:113]
	v_mfma_f32_16x16x32_bf16 v[106:109], v[176:179], v[184:187], v[106:109]
	v_mfma_f32_16x16x32_bf16 v[90:93], v[176:179], v[192:195], v[90:93]
	v_mfma_f32_16x16x32_bf16 v[94:97], v[168:171], v[192:195], v[94:97]
	v_mfma_f32_16x16x32_bf16 v[78:81], v[168:171], v[200:203], v[78:81]
	v_mfma_f32_16x16x32_bf16 v[74:77], v[176:179], v[200:203], v[74:77]
	v_mfma_f32_16x16x32_bf16 v[66:69], v[176:179], v[208:211], v[66:69]
	v_mfma_f32_16x16x32_bf16 v[70:73], v[168:171], v[208:211], v[70:73]
	s_setprio 0
	s_barrier
	s_mov_b32 m0, s78
	v_lshl_add_u64 v[148:149], s[72:73], 0, v[0:1]
	ds_read_b128 v[180:183], v139 offset:16384
	ds_read_b128 v[184:187], v139 offset:17408
	ds_read_b128 v[188:191], v139 offset:18432
	ds_read_b128 v[192:195], v139 offset:19456
	ds_read_b128 v[196:199], v139 offset:20480
	ds_read_b128 v[200:203], v139 offset:21504
	ds_read_b128 v[204:207], v139 offset:22528
	ds_read_b128 v[208:211], v139 offset:23552
	global_load_lds_dwordx4 v[148:149], off
	v_lshl_add_u64 v[150:151], s[72:73], 0, v[130:131]
	s_mov_b32 m0, s91
	v_lshl_add_u64 v[212:213], s[74:75], 0, v[0:1]
	global_load_lds_dwordx4 v[150:151], off
	s_mov_b32 m0, s79
	v_lshl_add_u64 v[214:215], s[60:61], 0, v[132:133]
	global_load_lds_dwordx4 v[212:213], off
	s_mov_b32 m0, s90
	v_lshl_add_u64 v[212:213], s[74:75], 0, v[130:131]
	global_load_lds_dwordx4 v[212:213], off
	s_mov_b32 m0, s42
	v_lshl_add_u64 v[212:213], s[60:61], 0, v[134:135]
	global_load_lds_dwordx4 v[212:213], off
	s_mov_b32 m0, s43
	s_nop 0
	global_load_lds_dwordx4 v[214:215], off
	s_waitcnt vmcnt(8)
	s_waitcnt lgkmcnt(0)
	s_barrier
	s_setprio 1
	v_mfma_f32_16x16x32_bf16 v[62:65], v[140:143], v[180:183], v[62:65]
	v_mfma_f32_16x16x32_bf16 v[58:61], v[156:159], v[180:183], v[58:61]
	v_mfma_f32_16x16x32_bf16 v[50:53], v[156:159], v[188:191], v[50:53]
	v_mfma_f32_16x16x32_bf16 v[54:57], v[140:143], v[188:191], v[54:57]
	v_mfma_f32_16x16x32_bf16 v[38:41], v[140:143], v[196:199], v[38:41]
	v_mfma_f32_16x16x32_bf16 v[34:37], v[156:159], v[196:199], v[34:37]
	v_mfma_f32_16x16x32_bf16 v[18:21], v[156:159], v[204:207], v[18:21]
	v_mfma_f32_16x16x32_bf16 v[22:25], v[140:143], v[204:207], v[22:25]
	v_mfma_f32_16x16x32_bf16 v[62:65], v[144:147], v[184:187], v[62:65]
	v_mfma_f32_16x16x32_bf16 v[58:61], v[160:163], v[184:187], v[58:61]
	v_mfma_f32_16x16x32_bf16 v[50:53], v[160:163], v[192:195], v[50:53]
	v_mfma_f32_16x16x32_bf16 v[54:57], v[144:147], v[192:195], v[54:57]
	v_mfma_f32_16x16x32_bf16 v[38:41], v[144:147], v[200:203], v[38:41]
	v_mfma_f32_16x16x32_bf16 v[34:37], v[160:163], v[200:203], v[34:37]
	v_mfma_f32_16x16x32_bf16 v[18:21], v[160:163], v[208:211], v[18:21]
	v_mfma_f32_16x16x32_bf16 v[22:25], v[144:147], v[208:211], v[22:25]
	v_mfma_f32_16x16x32_bf16 v[46:49], v[164:167], v[180:183], v[46:49]
	v_mfma_f32_16x16x32_bf16 v[42:45], v[172:175], v[180:183], v[42:45]
	v_mfma_f32_16x16x32_bf16 v[26:29], v[172:175], v[188:191], v[26:29]
	v_mfma_f32_16x16x32_bf16 v[30:33], v[164:167], v[188:191], v[30:33]
	v_mfma_f32_16x16x32_bf16 v[14:17], v[164:167], v[196:199], v[14:17]
	v_mfma_f32_16x16x32_bf16 v[10:13], v[172:175], v[196:199], v[10:13]
	v_mfma_f32_16x16x32_bf16 v[2:5], v[172:175], v[204:207], v[2:5]
	v_mfma_f32_16x16x32_bf16 v[6:9], v[164:167], v[204:207], v[6:9]
	v_mfma_f32_16x16x32_bf16 v[46:49], v[168:171], v[184:187], v[46:49]
	v_mfma_f32_16x16x32_bf16 v[42:45], v[176:179], v[184:187], v[42:45]
	v_mfma_f32_16x16x32_bf16 v[26:29], v[176:179], v[192:195], v[26:29]
	v_mfma_f32_16x16x32_bf16 v[30:33], v[168:171], v[192:195], v[30:33]
	v_mfma_f32_16x16x32_bf16 v[14:17], v[168:171], v[200:203], v[14:17]
	v_mfma_f32_16x16x32_bf16 v[10:13], v[176:179], v[200:203], v[10:13]
	v_mfma_f32_16x16x32_bf16 v[2:5], v[176:179], v[208:211], v[2:5]
	v_mfma_f32_16x16x32_bf16 v[6:9], v[168:171], v[208:211], v[6:9]
	s_setprio 0
	s_barrier
	v_add_u32_e32 v160, s97, v137
	v_add_u32_e32 v176, s83, v137
	ds_read_b128 v[140:143], v160
	ds_read_b128 v[144:147], v160 offset:1024
	ds_read_b128 v[156:159], v160 offset:2048
	ds_read_b128 v[160:163], v160 offset:3072
	ds_read_b128 v[164:167], v176
	ds_read_b128 v[168:171], v176 offset:1024
	ds_read_b128 v[172:175], v176 offset:2048
	ds_read_b128 v[176:179], v176 offset:3072
	s_mov_b32 m0, s44
	v_lshl_add_u64 v[216:217], s[26:27], 0, v[134:135]
	ds_read_b128 v[180:183], v139 offset:32768
	ds_read_b128 v[184:187], v139 offset:33792
	ds_read_b128 v[188:191], v139 offset:34816
	ds_read_b128 v[192:195], v139 offset:35840
	ds_read_b128 v[196:199], v139 offset:36864
	ds_read_b128 v[200:203], v139 offset:37888
	ds_read_b128 v[204:207], v139 offset:38912
	ds_read_b128 v[208:211], v139 offset:39936
	global_load_lds_dwordx4 v[216:217], off
	s_mov_b32 m0, s45
	v_lshl_add_u64 v[216:217], s[26:27], 0, v[132:133]
	global_load_lds_dwordx4 v[216:217], off
	s_waitcnt vmcnt(8)
	s_waitcnt lgkmcnt(0)
	s_barrier
	s_setprio 1
	v_mfma_f32_16x16x32_bf16 v[126:129], v[140:143], v[180:183], v[126:129]
	v_mfma_f32_16x16x32_bf16 v[122:125], v[156:159], v[180:183], v[122:125]
	v_mfma_f32_16x16x32_bf16 v[114:117], v[156:159], v[188:191], v[114:117]
	v_mfma_f32_16x16x32_bf16 v[118:121], v[140:143], v[188:191], v[118:121]
	v_mfma_f32_16x16x32_bf16 v[102:105], v[140:143], v[196:199], v[102:105]
	v_mfma_f32_16x16x32_bf16 v[98:101], v[156:159], v[196:199], v[98:101]
	v_mfma_f32_16x16x32_bf16 v[82:85], v[156:159], v[204:207], v[82:85]
	v_mfma_f32_16x16x32_bf16 v[86:89], v[140:143], v[204:207], v[86:89]
	v_mfma_f32_16x16x32_bf16 v[126:129], v[144:147], v[184:187], v[126:129]
	v_mfma_f32_16x16x32_bf16 v[122:125], v[160:163], v[184:187], v[122:125]
	v_mfma_f32_16x16x32_bf16 v[114:117], v[160:163], v[192:195], v[114:117]
	v_mfma_f32_16x16x32_bf16 v[118:121], v[144:147], v[192:195], v[118:121]
	v_mfma_f32_16x16x32_bf16 v[102:105], v[144:147], v[200:203], v[102:105]
	v_mfma_f32_16x16x32_bf16 v[98:101], v[160:163], v[200:203], v[98:101]
	v_mfma_f32_16x16x32_bf16 v[82:85], v[160:163], v[208:211], v[82:85]
	v_mfma_f32_16x16x32_bf16 v[86:89], v[144:147], v[208:211], v[86:89]
	v_mfma_f32_16x16x32_bf16 v[110:113], v[164:167], v[180:183], v[110:113]
	v_mfma_f32_16x16x32_bf16 v[106:109], v[172:175], v[180:183], v[106:109]
	v_mfma_f32_16x16x32_bf16 v[90:93], v[172:175], v[188:191], v[90:93]
	v_mfma_f32_16x16x32_bf16 v[94:97], v[164:167], v[188:191], v[94:97]
	v_mfma_f32_16x16x32_bf16 v[78:81], v[164:167], v[196:199], v[78:81]
	v_mfma_f32_16x16x32_bf16 v[74:77], v[172:175], v[196:199], v[74:77]
	v_mfma_f32_16x16x32_bf16 v[66:69], v[172:175], v[204:207], v[66:69]
	v_mfma_f32_16x16x32_bf16 v[70:73], v[164:167], v[204:207], v[70:73]
	v_mfma_f32_16x16x32_bf16 v[110:113], v[168:171], v[184:187], v[110:113]
	v_mfma_f32_16x16x32_bf16 v[106:109], v[176:179], v[184:187], v[106:109]
	v_mfma_f32_16x16x32_bf16 v[90:93], v[176:179], v[192:195], v[90:93]
	v_mfma_f32_16x16x32_bf16 v[94:97], v[168:171], v[192:195], v[94:97]
	v_mfma_f32_16x16x32_bf16 v[78:81], v[168:171], v[200:203], v[78:81]
	v_mfma_f32_16x16x32_bf16 v[74:77], v[176:179], v[200:203], v[74:77]
	v_mfma_f32_16x16x32_bf16 v[66:69], v[176:179], v[208:211], v[66:69]
	v_mfma_f32_16x16x32_bf16 v[70:73], v[168:171], v[208:211], v[70:73]
	s_setprio 0
	s_barrier
	s_mov_b32 m0, s53
	v_lshl_add_u64 v[148:149], v[148:149], 0, s[70:71]
	ds_read_b128 v[180:183], v139 offset:49152
	ds_read_b128 v[184:187], v139 offset:50176
	ds_read_b128 v[188:191], v139 offset:51200
	ds_read_b128 v[192:195], v139 offset:52224
	ds_read_b128 v[196:199], v139 offset:53248
	ds_read_b128 v[200:203], v139 offset:54272
	ds_read_b128 v[204:207], v139 offset:55296
	ds_read_b128 v[208:211], v139 offset:56320
	global_load_lds_dwordx4 v[148:149], off
	s_mov_b32 m0, s9
	v_lshl_add_u64 v[148:149], v[150:151], 0, s[70:71]
	global_load_lds_dwordx4 v[148:149], off
	s_mov_b32 m0, s96
	v_lshl_add_u64 v[148:149], s[38:39], 0, v[0:1]
	global_load_lds_dwordx4 v[148:149], off
	s_mov_b32 m0, s92
	v_lshl_add_u64 v[148:149], s[38:39], 0, v[130:131]
	global_load_lds_dwordx4 v[148:149], off
	s_mov_b32 m0, s46
	v_lshl_add_u64 v[148:149], v[212:213], 0, s[70:71]
	global_load_lds_dwordx4 v[148:149], off
	s_mov_b32 m0, s47
	v_lshl_add_u64 v[148:149], v[214:215], 0, s[70:71]
	global_load_lds_dwordx4 v[148:149], off
	s_waitcnt vmcnt(8)
	s_waitcnt lgkmcnt(0)
	s_barrier
	s_setprio 1
	v_mfma_f32_16x16x32_bf16 v[62:65], v[140:143], v[180:183], v[62:65]
	v_mfma_f32_16x16x32_bf16 v[58:61], v[156:159], v[180:183], v[58:61]
	v_mfma_f32_16x16x32_bf16 v[50:53], v[156:159], v[188:191], v[50:53]
	v_mfma_f32_16x16x32_bf16 v[54:57], v[140:143], v[188:191], v[54:57]
	v_mfma_f32_16x16x32_bf16 v[38:41], v[140:143], v[196:199], v[38:41]
	v_mfma_f32_16x16x32_bf16 v[34:37], v[156:159], v[196:199], v[34:37]
	v_mfma_f32_16x16x32_bf16 v[18:21], v[156:159], v[204:207], v[18:21]
	v_mfma_f32_16x16x32_bf16 v[22:25], v[140:143], v[204:207], v[22:25]
	v_mfma_f32_16x16x32_bf16 v[62:65], v[144:147], v[184:187], v[62:65]
	v_mfma_f32_16x16x32_bf16 v[58:61], v[160:163], v[184:187], v[58:61]
	v_mfma_f32_16x16x32_bf16 v[50:53], v[160:163], v[192:195], v[50:53]
	v_mfma_f32_16x16x32_bf16 v[54:57], v[144:147], v[192:195], v[54:57]
	v_mfma_f32_16x16x32_bf16 v[38:41], v[144:147], v[200:203], v[38:41]
	v_mfma_f32_16x16x32_bf16 v[34:37], v[160:163], v[200:203], v[34:37]
	v_mfma_f32_16x16x32_bf16 v[18:21], v[160:163], v[208:211], v[18:21]
	v_mfma_f32_16x16x32_bf16 v[22:25], v[144:147], v[208:211], v[22:25]
	v_mfma_f32_16x16x32_bf16 v[46:49], v[164:167], v[180:183], v[46:49]
	v_mfma_f32_16x16x32_bf16 v[42:45], v[172:175], v[180:183], v[42:45]
	v_mfma_f32_16x16x32_bf16 v[26:29], v[172:175], v[188:191], v[26:29]
	v_mfma_f32_16x16x32_bf16 v[30:33], v[164:167], v[188:191], v[30:33]
	v_mfma_f32_16x16x32_bf16 v[14:17], v[164:167], v[196:199], v[14:17]
	v_mfma_f32_16x16x32_bf16 v[10:13], v[172:175], v[196:199], v[10:13]
	v_mfma_f32_16x16x32_bf16 v[2:5], v[172:175], v[204:207], v[2:5]
	v_mfma_f32_16x16x32_bf16 v[6:9], v[164:167], v[204:207], v[6:9]
	v_mfma_f32_16x16x32_bf16 v[46:49], v[168:171], v[184:187], v[46:49]
	v_mfma_f32_16x16x32_bf16 v[42:45], v[176:179], v[184:187], v[42:45]
	v_mfma_f32_16x16x32_bf16 v[26:29], v[176:179], v[192:195], v[26:29]
	v_mfma_f32_16x16x32_bf16 v[30:33], v[168:171], v[192:195], v[30:33]
	v_mfma_f32_16x16x32_bf16 v[14:17], v[168:171], v[200:203], v[14:17]
	v_mfma_f32_16x16x32_bf16 v[10:13], v[176:179], v[200:203], v[10:13]
	v_mfma_f32_16x16x32_bf16 v[2:5], v[176:179], v[208:211], v[2:5]
	v_mfma_f32_16x16x32_bf16 v[6:9], v[168:171], v[208:211], v[6:9]
	s_setprio 0
	s_barrier
	s_movk_i32 s9, 0x100
	s_andn2_b64 vcc, exec, s[4:5]
	s_mov_b64 s[38:39], -1
	s_mov_b64 s[4:5], 0
	s_cbranch_vccz .LBB0_376
	s_and_b64 vcc, exec, s[14:15]
	s_cbranch_vccz .LBB0_379
	s_barrier

.LBB0_393:
	s_ashr_i32 s19, s18, 31
	s_lshl_b64 s[24:25], s[18:19], 16
	s_add_u32 s24, s29, s24
	s_addc_u32 s25, s38, s25
	s_and_b64 s[4:5], s[4:5], exec
	s_cselect_b32 s5, s25, s27
	s_cselect_b32 s4, s24, s26
	s_add_i32 s19, 0, 0x10000
	s_add_i32 s48, 0, 0x14000
	v_add_u32_e32 v14, s19, v137
	v_add_u32_e32 v30, s48, v137
	.p2align 6
	ds_read_b128 v[2:5], v14
	ds_read_b128 v[6:9], v14 offset:1024
	ds_read_b128 v[10:13], v14 offset:2048
	ds_read_b128 v[14:17], v14 offset:3072
	ds_read_b128 v[18:21], v30
	ds_read_b128 v[22:25], v30 offset:1024
	ds_read_b128 v[26:29], v30 offset:2048
	ds_read_b128 v[30:33], v30 offset:3072
	s_add_u32 s26, s36, 0x58080
	s_addc_u32 s27, s37, 0
	v_lshl_add_u64 v[66:67], s[26:27], 0, v[134:135]
	s_add_i32 m0, s40, 0xc000
	ds_read_b128 v[34:37], v139
	ds_read_b128 v[38:41], v139 offset:1024
	ds_read_b128 v[42:45], v139 offset:2048
	ds_read_b128 v[46:49], v139 offset:3072
	ds_read_b128 v[50:53], v139 offset:4096
	ds_read_b128 v[54:57], v139 offset:5120
	ds_read_b128 v[58:61], v139 offset:6144
	ds_read_b128 v[62:65], v139 offset:7168
	global_load_lds_dwordx4 v[66:67], off
	s_add_i32 m0, s40, 0xe000
	v_lshl_add_u64 v[66:67], s[26:27], 0, v[132:133]
	global_load_lds_dwordx4 v[66:67], off
	s_waitcnt vmcnt(8)
	s_waitcnt lgkmcnt(0)
	s_barrier
	s_setprio 1
	v_mfma_f32_16x16x32_bf16 v[66:69], v[2:5], v[34:37], 0
	v_mfma_f32_16x16x32_bf16 v[70:73], v[10:13], v[34:37], 0
	v_mfma_f32_16x16x32_bf16 v[78:81], v[10:13], v[42:45], 0
	v_mfma_f32_16x16x32_bf16 v[74:77], v[2:5], v[42:45], 0
	v_mfma_f32_16x16x32_bf16 v[82:85], v[2:5], v[50:53], 0
	v_mfma_f32_16x16x32_bf16 v[86:89], v[10:13], v[50:53], 0
	v_mfma_f32_16x16x32_bf16 v[94:97], v[10:13], v[58:61], 0
	v_mfma_f32_16x16x32_bf16 v[90:93], v[2:5], v[58:61], 0
	v_mfma_f32_16x16x32_bf16 v[66:69], v[6:9], v[38:41], v[66:69]
	v_mfma_f32_16x16x32_bf16 v[70:73], v[14:17], v[38:41], v[70:73]
	v_mfma_f32_16x16x32_bf16 v[78:81], v[14:17], v[46:49], v[78:81]
	v_mfma_f32_16x16x32_bf16 v[74:77], v[6:9], v[46:49], v[74:77]
	v_mfma_f32_16x16x32_bf16 v[82:85], v[6:9], v[54:57], v[82:85]
	v_mfma_f32_16x16x32_bf16 v[86:89], v[14:17], v[54:57], v[86:89]
	v_mfma_f32_16x16x32_bf16 v[94:97], v[14:17], v[62:65], v[94:97]
	v_mfma_f32_16x16x32_bf16 v[90:93], v[6:9], v[62:65], v[90:93]
	v_mfma_f32_16x16x32_bf16 v[98:101], v[18:21], v[34:37], 0
	v_mfma_f32_16x16x32_bf16 v[34:37], v[26:29], v[34:37], 0
	v_mfma_f32_16x16x32_bf16 v[98:101], v[22:25], v[38:41], v[98:101]
	v_mfma_f32_16x16x32_bf16 v[34:37], v[30:33], v[38:41], v[34:37]
	v_mfma_f32_16x16x32_bf16 v[38:41], v[18:21], v[42:45], 0
	v_mfma_f32_16x16x32_bf16 v[42:45], v[26:29], v[42:45], 0
	v_mfma_f32_16x16x32_bf16 v[102:105], v[30:33], v[46:49], v[42:45]
	v_mfma_f32_16x16x32_bf16 v[42:45], v[18:21], v[50:53], 0
	v_mfma_f32_16x16x32_bf16 v[114:117], v[22:25], v[54:57], v[42:45]
	v_mfma_f32_16x16x32_bf16 v[42:45], v[26:29], v[50:53], 0
	v_mfma_f32_16x16x32_bf16 v[50:53], v[30:33], v[54:57], v[42:45]
	v_mfma_f32_16x16x32_bf16 v[42:45], v[18:21], v[58:61], 0
	v_mfma_f32_16x16x32_bf16 v[54:57], v[22:25], v[62:65], v[42:45]
	v_mfma_f32_16x16x32_bf16 v[42:45], v[26:29], v[58:61], 0
	v_mfma_f32_16x16x32_bf16 v[38:41], v[22:25], v[46:49], v[38:41]
	v_mfma_f32_16x16x32_bf16 v[58:61], v[30:33], v[62:65], v[42:45]
	s_setprio 0
	s_barrier
	s_add_i32 s19, s19, s39
	v_lshl_add_u64 v[148:149], s[4:5], 0, v[0:1]
	s_mov_b32 m0, s19
	s_nop 0
	ds_read_b128 v[42:45], v139 offset:16384
	ds_read_b128 v[46:49], v139 offset:17408
	ds_read_b128 v[62:65], v139 offset:18432
	ds_read_b128 v[106:109], v139 offset:19456
	ds_read_b128 v[110:113], v139 offset:20480
	ds_read_b128 v[118:121], v139 offset:21504
	ds_read_b128 v[122:125], v139 offset:22528
	ds_read_b128 v[126:129], v139 offset:23552
	global_load_lds_dwordx4 v[148:149], off
	s_add_i32 m0, s19, 0x2000
	s_add_u32 s26, s4, 0x8000
	v_lshl_add_u64 v[150:151], s[4:5], 0, v[130:131]
	s_addc_u32 s27, s5, 0
	s_add_i32 s19, s48, s39
	global_load_lds_dwordx4 v[150:151], off
	v_lshl_add_u64 v[140:141], s[26:27], 0, v[0:1]
	s_mov_b32 m0, s19
	v_lshl_add_u64 v[252:253], s[22:23], 0, v[134:135]
	global_load_lds_dwordx4 v[140:141], off
	v_lshl_add_u64 v[140:141], s[26:27], 0, v[130:131]
	s_add_i32 m0, s19, 0x2000
	v_lshl_add_u64 v[242:243], s[22:23], 0, v[132:133]
	global_load_lds_dwordx4 v[140:141], off
	s_mov_b32 m0, s40
	s_nop 0
	global_load_lds_dwordx4 v[252:253], off
	s_mov_b32 m0, s41
	s_nop 0
	global_load_lds_dwordx4 v[242:243], off
	s_waitcnt vmcnt(8)
	s_waitcnt lgkmcnt(0)
	s_barrier
	s_setprio 1
	v_mfma_f32_16x16x32_bf16 v[140:143], v[2:5], v[42:45], 0
	v_mfma_f32_16x16x32_bf16 v[156:159], v[2:5], v[62:65], 0
	v_mfma_f32_16x16x32_bf16 v[164:167], v[2:5], v[110:113], 0
	v_mfma_f32_16x16x32_bf16 v[2:5], v[2:5], v[122:125], 0
	v_mfma_f32_16x16x32_bf16 v[140:143], v[6:9], v[46:49], v[140:143]
	v_mfma_f32_16x16x32_bf16 v[156:159], v[6:9], v[106:109], v[156:159]
	v_mfma_f32_16x16x32_bf16 v[164:167], v[6:9], v[118:121], v[164:167]
	v_mfma_f32_16x16x32_bf16 v[2:5], v[6:9], v[126:129], v[2:5]
	v_mfma_f32_16x16x32_bf16 v[6:9], v[10:13], v[122:125], 0
	v_mfma_f32_16x16x32_bf16 v[144:147], v[10:13], v[42:45], 0
	v_mfma_f32_16x16x32_bf16 v[160:163], v[10:13], v[62:65], 0
	v_mfma_f32_16x16x32_bf16 v[168:171], v[10:13], v[110:113], 0
	v_mfma_f32_16x16x32_bf16 v[6:9], v[14:17], v[126:129], v[6:9]
	v_mfma_f32_16x16x32_bf16 v[144:147], v[14:17], v[46:49], v[144:147]
	v_mfma_f32_16x16x32_bf16 v[160:163], v[14:17], v[106:109], v[160:163]
	v_mfma_f32_16x16x32_bf16 v[168:171], v[14:17], v[118:121], v[168:171]
	v_mfma_f32_16x16x32_bf16 v[10:13], v[18:21], v[42:45], 0
	v_mfma_f32_16x16x32_bf16 v[172:175], v[22:25], v[46:49], v[10:13]
	v_mfma_f32_16x16x32_bf16 v[10:13], v[26:29], v[42:45], 0
	v_mfma_f32_16x16x32_bf16 v[176:179], v[30:33], v[46:49], v[10:13]
	v_mfma_f32_16x16x32_bf16 v[10:13], v[18:21], v[62:65], 0
	v_mfma_f32_16x16x32_bf16 v[180:183], v[22:25], v[106:109], v[10:13]
	v_mfma_f32_16x16x32_bf16 v[10:13], v[26:29], v[62:65], 0
	v_mfma_f32_16x16x32_bf16 v[184:187], v[30:33], v[106:109], v[10:13]
	v_mfma_f32_16x16x32_bf16 v[10:13], v[18:21], v[110:113], 0
	v_mfma_f32_16x16x32_bf16 v[188:191], v[22:25], v[118:121], v[10:13]
	v_mfma_f32_16x16x32_bf16 v[10:13], v[26:29], v[110:113], 0
	v_mfma_f32_16x16x32_bf16 v[192:195], v[30:33], v[118:121], v[10:13]
	v_mfma_f32_16x16x32_bf16 v[10:13], v[18:21], v[122:125], 0
	v_mfma_f32_16x16x32_bf16 v[18:21], v[22:25], v[126:129], v[10:13]
	v_mfma_f32_16x16x32_bf16 v[10:13], v[26:29], v[122:125], 0
	v_mfma_f32_16x16x32_bf16 v[22:25], v[30:33], v[126:129], v[10:13]
	s_setprio 0
	s_barrier
	s_add_i32 s19, 0, 0x18000
	s_nop 3
	v_add_u32_e32 v10, s19, v137
	s_add_i32 s36, 0, 0x1c000
	ds_read_b128 v[118:121], v10
	ds_read_b128 v[196:199], v10 offset:1024
	ds_read_b128 v[200:203], v10 offset:2048
	ds_read_b128 v[204:207], v10 offset:3072
	v_add_u32_e32 v10, s36, v137
	ds_read_b128 v[208:211], v10
	ds_read_b128 v[212:215], v10 offset:1024
	ds_read_b128 v[216:219], v10 offset:2048
	ds_read_b128 v[220:223], v10 offset:3072
	s_add_u32 s26, s22, 0x58000
	s_addc_u32 s27, s23, 0
	s_mov_b32 m0, s42
	v_lshl_add_u64 v[10:11], s[26:27], 0, v[134:135]
	ds_read_b128 v[26:29], v139 offset:32768
	ds_read_b128 v[30:33], v139 offset:33792
	ds_read_b128 v[62:65], v139 offset:34816
	ds_read_b128 v[224:227], v139 offset:35840
	ds_read_b128 v[228:231], v139 offset:36864
	ds_read_b128 v[232:235], v139 offset:37888
	ds_read_b128 v[236:239], v139 offset:38912
	ds_read_b128 v[248:251], v139 offset:39936
	global_load_lds_dwordx4 v[10:11], off
	s_mov_b32 m0, s43
	v_lshl_add_u64 v[10:11], s[26:27], 0, v[132:133]
	global_load_lds_dwordx4 v[10:11], off
	s_waitcnt vmcnt(8)
	s_waitcnt lgkmcnt(0)
	s_barrier
	s_setprio 1
	v_mfma_f32_16x16x32_bf16 v[10:13], v[118:121], v[26:29], v[66:69]
	v_mfma_f32_16x16x32_bf16 v[106:109], v[196:199], v[30:33], v[10:13]
	v_mfma_f32_16x16x32_bf16 v[10:13], v[200:203], v[26:29], v[70:73]
	v_mfma_f32_16x16x32_bf16 v[110:113], v[204:207], v[30:33], v[10:13]
	v_mfma_f32_16x16x32_bf16 v[10:13], v[118:121], v[62:65], v[74:77]
	v_mfma_f32_16x16x32_bf16 v[74:77], v[196:199], v[224:227], v[10:13]
	v_mfma_f32_16x16x32_bf16 v[10:13], v[200:203], v[62:65], v[78:81]
	v_mfma_f32_16x16x32_bf16 v[78:81], v[204:207], v[224:227], v[10:13]
	v_mfma_f32_16x16x32_bf16 v[10:13], v[118:121], v[228:231], v[82:85]
	v_mfma_f32_16x16x32_bf16 v[42:45], v[196:199], v[232:235], v[10:13]
	v_mfma_f32_16x16x32_bf16 v[10:13], v[200:203], v[228:231], v[86:89]
	v_mfma_f32_16x16x32_bf16 v[46:49], v[204:207], v[232:235], v[10:13]
	v_mfma_f32_16x16x32_bf16 v[10:13], v[118:121], v[236:239], v[90:93]
	v_mfma_f32_16x16x32_bf16 v[14:17], v[200:203], v[236:239], v[94:97]
	v_mfma_f32_16x16x32_bf16 v[10:13], v[196:199], v[248:251], v[10:13]
	v_mfma_f32_16x16x32_bf16 v[14:17], v[204:207], v[248:251], v[14:17]
	v_mfma_f32_16x16x32_bf16 v[66:69], v[208:211], v[26:29], v[98:101]
	v_mfma_f32_16x16x32_bf16 v[26:29], v[216:219], v[26:29], v[34:37]
	v_mfma_f32_16x16x32_bf16 v[126:129], v[220:223], v[30:33], v[26:29]
	v_mfma_f32_16x16x32_bf16 v[26:29], v[208:211], v[62:65], v[38:41]
	v_mfma_f32_16x16x32_bf16 v[98:101], v[212:215], v[224:227], v[26:29]
	v_mfma_f32_16x16x32_bf16 v[26:29], v[216:219], v[62:65], v[102:105]
	v_mfma_f32_16x16x32_bf16 v[102:105], v[220:223], v[224:227], v[26:29]
	v_mfma_f32_16x16x32_bf16 v[26:29], v[208:211], v[228:231], v[114:117]
	v_mfma_f32_16x16x32_bf16 v[122:125], v[212:215], v[30:33], v[66:69]
	v_mfma_f32_16x16x32_bf16 v[66:69], v[212:215], v[232:235], v[26:29]
	v_mfma_f32_16x16x32_bf16 v[26:29], v[216:219], v[228:231], v[50:53]
	v_mfma_f32_16x16x32_bf16 v[70:73], v[220:223], v[232:235], v[26:29]
	v_mfma_f32_16x16x32_bf16 v[26:29], v[208:211], v[236:239], v[54:57]
	v_mfma_f32_16x16x32_bf16 v[34:37], v[212:215], v[248:251], v[26:29]
	v_mfma_f32_16x16x32_bf16 v[26:29], v[216:219], v[236:239], v[58:61]
	v_mfma_f32_16x16x32_bf16 v[38:41], v[220:223], v[248:251], v[26:29]
	s_setprio 0
	s_barrier
	s_add_i32 s19, s19, s39
	s_nop 3
	v_lshl_add_u64 v[26:27], v[148:149], 0, s[70:71]
	s_mov_b32 m0, s19
	ds_read_b128 v[50:53], v139 offset:49152
	ds_read_b128 v[54:57], v139 offset:50176
	ds_read_b128 v[86:89], v139 offset:51200
	ds_read_b128 v[224:227], v139 offset:52224
	ds_read_b128 v[228:231], v139 offset:53248
	ds_read_b128 v[232:235], v139 offset:54272
	ds_read_b128 v[236:239], v139 offset:55296
	ds_read_b128 v[248:251], v139 offset:56320
	global_load_lds_dwordx4 v[26:27], off
	s_add_i32 m0, s19, 0x2000
	s_add_u32 s4, s4, 0x8080
	v_lshl_add_u64 v[26:27], v[150:151], 0, s[70:71]
	s_addc_u32 s5, s5, 0
	s_add_i32 s19, s36, s39
	global_load_lds_dwordx4 v[26:27], off
	s_mov_b32 m0, s19
	v_lshl_add_u64 v[26:27], s[4:5], 0, v[0:1]
	global_load_lds_dwordx4 v[26:27], off
	s_add_i32 m0, s19, 0x2000
	v_lshl_add_u64 v[26:27], s[4:5], 0, v[130:131]
	global_load_lds_dwordx4 v[26:27], off
	s_mov_b32 m0, s44
	v_lshl_add_u64 v[26:27], v[252:253], 0, s[70:71]
	global_load_lds_dwordx4 v[26:27], off
	s_mov_b32 m0, s45
	v_lshl_add_u64 v[26:27], v[242:243], 0, s[70:71]
	global_load_lds_dwordx4 v[26:27], off
	s_waitcnt vmcnt(8)
	s_waitcnt lgkmcnt(0)
	s_barrier
	s_setprio 1
	v_mfma_f32_16x16x32_bf16 v[26:29], v[118:121], v[50:53], v[140:143]
	v_mfma_f32_16x16x32_bf16 v[90:93], v[196:199], v[54:57], v[26:29]
	v_mfma_f32_16x16x32_bf16 v[26:29], v[200:203], v[50:53], v[144:147]
	v_mfma_f32_16x16x32_bf16 v[94:97], v[204:207], v[54:57], v[26:29]
	v_mfma_f32_16x16x32_bf16 v[26:29], v[118:121], v[86:89], v[156:159]
	v_mfma_f32_16x16x32_bf16 v[58:61], v[196:199], v[224:227], v[26:29]
	v_mfma_f32_16x16x32_bf16 v[26:29], v[200:203], v[86:89], v[160:163]
	v_mfma_f32_16x16x32_bf16 v[62:65], v[204:207], v[224:227], v[26:29]
	v_mfma_f32_16x16x32_bf16 v[26:29], v[118:121], v[228:231], v[164:167]
	v_mfma_f32_16x16x32_bf16 v[30:33], v[200:203], v[228:231], v[168:171]
	v_mfma_f32_16x16x32_bf16 v[2:5], v[118:121], v[236:239], v[2:5]
	v_mfma_f32_16x16x32_bf16 v[6:9], v[200:203], v[236:239], v[6:9]
	v_mfma_f32_16x16x32_bf16 v[26:29], v[196:199], v[232:235], v[26:29]
	v_mfma_f32_16x16x32_bf16 v[30:33], v[204:207], v[232:235], v[30:33]
	v_mfma_f32_16x16x32_bf16 v[2:5], v[196:199], v[248:251], v[2:5]
	v_mfma_f32_16x16x32_bf16 v[6:9], v[204:207], v[248:251], v[6:9]
	v_mfma_f32_16x16x32_bf16 v[82:85], v[208:211], v[50:53], v[172:175]
	v_mfma_f32_16x16x32_bf16 v[50:53], v[216:219], v[50:53], v[176:179]
	v_mfma_f32_16x16x32_bf16 v[118:121], v[220:223], v[54:57], v[50:53]
	v_mfma_f32_16x16x32_bf16 v[50:53], v[208:211], v[86:89], v[180:183]
	v_mfma_f32_16x16x32_bf16 v[114:117], v[212:215], v[54:57], v[82:85]
	v_mfma_f32_16x16x32_bf16 v[82:85], v[212:215], v[224:227], v[50:53]
	v_mfma_f32_16x16x32_bf16 v[50:53], v[216:219], v[86:89], v[184:187]
	v_mfma_f32_16x16x32_bf16 v[86:89], v[220:223], v[224:227], v[50:53]
	v_mfma_f32_16x16x32_bf16 v[50:53], v[208:211], v[228:231], v[188:191]
	v_mfma_f32_16x16x32_bf16 v[54:57], v[216:219], v[228:231], v[192:195]
	v_mfma_f32_16x16x32_bf16 v[18:21], v[208:211], v[236:239], v[18:21]
	v_mfma_f32_16x16x32_bf16 v[22:25], v[216:219], v[236:239], v[22:25]
	v_mfma_f32_16x16x32_bf16 v[50:53], v[212:215], v[232:235], v[50:53]
	v_mfma_f32_16x16x32_bf16 v[54:57], v[220:223], v[232:235], v[54:57]
	v_mfma_f32_16x16x32_bf16 v[18:21], v[212:215], v[248:251], v[18:21]
	v_mfma_f32_16x16x32_bf16 v[22:25], v[220:223], v[248:251], v[22:25]
	s_setprio 0
	s_barrier
	s_andn2_b64 vcc, exec, s[14:15]
	s_cbranch_vccnz .LBB0_395
	s_barrier

.LBB0_701:
	s_add_i32 s75, s26, 2
	s_add_u32 s9, s60, 0xfffc0080
	s_addc_u32 s27, s61, -1
	s_add_i32 s78, 0, 0x10000
	s_cmp_eq_u32 s19, s26
	s_cselect_b32 s73, s23, s27
	s_cselect_b32 s72, s22, s9
	s_cselect_b32 s27, s25, s29
	s_cselect_b32 s26, s24, s28
	s_add_i32 s9, 0, 0x14000
	s_waitcnt vmcnt(0)
	v_add_u32_e32 v142, s78, v177
	v_add_u32_e32 v148, s9, v177
	ds_read_b128 v[130:133], v142
	ds_read_b128 v[134:137], v142 offset:1024
	ds_read_b128 v[138:141], v142 offset:2048
	ds_read_b128 v[142:145], v142 offset:3072
	ds_read_b128 v[164:167], v148
	ds_read_b128 v[168:171], v148 offset:1024
	ds_read_b128 v[172:175], v148 offset:2048
	ds_read_b128 v[180:183], v148 offset:3072
	v_lshl_add_u64 v[148:149], s[60:61], 0, v[160:161]
	s_add_i32 m0, s37, 0xc000
	ds_read_b128 v[184:187], v179
	ds_read_b128 v[188:191], v179 offset:1024
	ds_read_b128 v[192:195], v179 offset:2048
	ds_read_b128 v[196:199], v179 offset:3072
	ds_read_b128 v[200:203], v179 offset:4096
	ds_read_b128 v[204:207], v179 offset:5120
	ds_read_b128 v[208:211], v179 offset:6144
	ds_read_b128 v[212:215], v179 offset:7168
	global_load_lds_dwordx4 v[148:149], off
	s_add_i32 m0, s37, 0xe000
	v_lshl_add_u64 v[148:149], s[60:61], 0, v[162:163]
	global_load_lds_dwordx4 v[148:149], off
	s_waitcnt vmcnt(8)
	s_waitcnt lgkmcnt(0)
	s_barrier
	s_setprio 1
	v_mfma_f32_16x16x32_bf16 v[126:129], v[130:133], v[184:187], v[126:129]
	v_mfma_f32_16x16x32_bf16 v[122:125], v[138:141], v[184:187], v[122:125]
	v_mfma_f32_16x16x32_bf16 v[106:109], v[138:141], v[192:195], v[106:109]
	v_mfma_f32_16x16x32_bf16 v[110:113], v[130:133], v[192:195], v[110:113]
	v_mfma_f32_16x16x32_bf16 v[94:97], v[130:133], v[200:203], v[94:97]
	v_mfma_f32_16x16x32_bf16 v[90:93], v[138:141], v[200:203], v[90:93]
	v_mfma_f32_16x16x32_bf16 v[74:77], v[138:141], v[208:211], v[74:77]
	v_mfma_f32_16x16x32_bf16 v[78:81], v[130:133], v[208:211], v[78:81]
	v_mfma_f32_16x16x32_bf16 v[126:129], v[134:137], v[188:191], v[126:129]
	v_mfma_f32_16x16x32_bf16 v[122:125], v[142:145], v[188:191], v[122:125]
	v_mfma_f32_16x16x32_bf16 v[106:109], v[142:145], v[196:199], v[106:109]
	v_mfma_f32_16x16x32_bf16 v[110:113], v[134:137], v[196:199], v[110:113]
	v_mfma_f32_16x16x32_bf16 v[94:97], v[134:137], v[204:207], v[94:97]
	v_mfma_f32_16x16x32_bf16 v[90:93], v[142:145], v[204:207], v[90:93]
	v_mfma_f32_16x16x32_bf16 v[74:77], v[142:145], v[212:215], v[74:77]
	v_mfma_f32_16x16x32_bf16 v[78:81], v[134:137], v[212:215], v[78:81]
	v_mfma_f32_16x16x32_bf16 v[118:121], v[164:167], v[184:187], v[118:121]
	v_mfma_f32_16x16x32_bf16 v[114:117], v[172:175], v[184:187], v[114:117]
	v_mfma_f32_16x16x32_bf16 v[98:101], v[172:175], v[192:195], v[98:101]
	v_mfma_f32_16x16x32_bf16 v[102:105], v[164:167], v[192:195], v[102:105]
	v_mfma_f32_16x16x32_bf16 v[86:89], v[164:167], v[200:203], v[86:89]
	v_mfma_f32_16x16x32_bf16 v[82:85], v[172:175], v[200:203], v[82:85]
	v_mfma_f32_16x16x32_bf16 v[66:69], v[172:175], v[208:211], v[66:69]
	v_mfma_f32_16x16x32_bf16 v[70:73], v[164:167], v[208:211], v[70:73]
	v_mfma_f32_16x16x32_bf16 v[118:121], v[168:171], v[188:191], v[118:121]
	v_mfma_f32_16x16x32_bf16 v[114:117], v[180:183], v[188:191], v[114:117]
	v_mfma_f32_16x16x32_bf16 v[98:101], v[180:183], v[196:199], v[98:101]
	v_mfma_f32_16x16x32_bf16 v[102:105], v[168:171], v[196:199], v[102:105]
	v_mfma_f32_16x16x32_bf16 v[86:89], v[168:171], v[204:207], v[86:89]
	v_mfma_f32_16x16x32_bf16 v[82:85], v[180:183], v[204:207], v[82:85]
	v_mfma_f32_16x16x32_bf16 v[66:69], v[180:183], v[212:215], v[66:69]
	v_mfma_f32_16x16x32_bf16 v[70:73], v[168:171], v[212:215], v[70:73]
	s_setprio 0
	s_barrier
	s_add_i32 s78, s78, s41
	v_lshl_add_u64 v[148:149], s[26:27], 0, v[0:1]
	s_mov_b32 m0, s78
	ds_read_b128 v[184:187], v179 offset:16384
	ds_read_b128 v[188:191], v179 offset:17408
	ds_read_b128 v[192:195], v179 offset:18432
	ds_read_b128 v[196:199], v179 offset:19456
	ds_read_b128 v[200:203], v179 offset:20480
	ds_read_b128 v[204:207], v179 offset:21504
	ds_read_b128 v[208:211], v179 offset:22528
	ds_read_b128 v[212:215], v179 offset:23552
	global_load_lds_dwordx4 v[148:149], off
	s_add_i32 m0, s78, 0x2000
	s_add_u32 s78, s26, 0x40000
	v_lshl_add_u64 v[150:151], s[26:27], 0, v[158:159]
	s_addc_u32 s79, s27, 0
	s_add_i32 s9, s9, s41
	global_load_lds_dwordx4 v[150:151], off
	v_lshl_add_u64 v[216:217], s[78:79], 0, v[0:1]
	s_mov_b32 m0, s9
	v_lshl_add_u64 v[218:219], s[72:73], 0, v[156:157]
	global_load_lds_dwordx4 v[216:217], off
	s_add_i32 m0, s9, 0x2000
	v_lshl_add_u64 v[216:217], s[78:79], 0, v[158:159]
	global_load_lds_dwordx4 v[216:217], off
	s_mov_b32 m0, s37
	v_lshl_add_u64 v[216:217], s[72:73], 0, v[146:147]
	global_load_lds_dwordx4 v[216:217], off
	s_mov_b32 m0, s39
	s_nop 0
	global_load_lds_dwordx4 v[218:219], off
	s_waitcnt vmcnt(8)
	s_waitcnt lgkmcnt(0)
	s_barrier
	s_setprio 1
	v_mfma_f32_16x16x32_bf16 v[62:65], v[130:133], v[184:187], v[62:65]
	v_mfma_f32_16x16x32_bf16 v[58:61], v[138:141], v[184:187], v[58:61]
	v_mfma_f32_16x16x32_bf16 v[42:45], v[138:141], v[192:195], v[42:45]
	v_mfma_f32_16x16x32_bf16 v[46:49], v[130:133], v[192:195], v[46:49]
	v_mfma_f32_16x16x32_bf16 v[30:33], v[130:133], v[200:203], v[30:33]
	v_mfma_f32_16x16x32_bf16 v[26:29], v[138:141], v[200:203], v[26:29]
	v_mfma_f32_16x16x32_bf16 v[10:13], v[138:141], v[208:211], v[10:13]
	v_mfma_f32_16x16x32_bf16 v[14:17], v[130:133], v[208:211], v[14:17]
	v_mfma_f32_16x16x32_bf16 v[62:65], v[134:137], v[188:191], v[62:65]
	v_mfma_f32_16x16x32_bf16 v[58:61], v[142:145], v[188:191], v[58:61]
	v_mfma_f32_16x16x32_bf16 v[42:45], v[142:145], v[196:199], v[42:45]
	v_mfma_f32_16x16x32_bf16 v[46:49], v[134:137], v[196:199], v[46:49]
	v_mfma_f32_16x16x32_bf16 v[30:33], v[134:137], v[204:207], v[30:33]
	v_mfma_f32_16x16x32_bf16 v[26:29], v[142:145], v[204:207], v[26:29]
	v_mfma_f32_16x16x32_bf16 v[10:13], v[142:145], v[212:215], v[10:13]
	v_mfma_f32_16x16x32_bf16 v[14:17], v[134:137], v[212:215], v[14:17]
	v_mfma_f32_16x16x32_bf16 v[54:57], v[164:167], v[184:187], v[54:57]
	v_mfma_f32_16x16x32_bf16 v[50:53], v[172:175], v[184:187], v[50:53]
	v_mfma_f32_16x16x32_bf16 v[34:37], v[172:175], v[192:195], v[34:37]
	v_mfma_f32_16x16x32_bf16 v[38:41], v[164:167], v[192:195], v[38:41]
	v_mfma_f32_16x16x32_bf16 v[22:25], v[164:167], v[200:203], v[22:25]
	v_mfma_f32_16x16x32_bf16 v[18:21], v[172:175], v[200:203], v[18:21]
	v_mfma_f32_16x16x32_bf16 v[2:5], v[172:175], v[208:211], v[2:5]
	v_mfma_f32_16x16x32_bf16 v[6:9], v[164:167], v[208:211], v[6:9]
	v_mfma_f32_16x16x32_bf16 v[54:57], v[168:171], v[188:191], v[54:57]
	v_mfma_f32_16x16x32_bf16 v[50:53], v[180:183], v[188:191], v[50:53]
	v_mfma_f32_16x16x32_bf16 v[34:37], v[180:183], v[196:199], v[34:37]
	v_mfma_f32_16x16x32_bf16 v[38:41], v[168:171], v[196:199], v[38:41]
	v_mfma_f32_16x16x32_bf16 v[22:25], v[168:171], v[204:207], v[22:25]
	v_mfma_f32_16x16x32_bf16 v[18:21], v[180:183], v[204:207], v[18:21]
	v_mfma_f32_16x16x32_bf16 v[2:5], v[180:183], v[212:215], v[2:5]
	v_mfma_f32_16x16x32_bf16 v[6:9], v[168:171], v[212:215], v[6:9]
	s_setprio 0
	s_barrier
	s_add_i32 s9, 0, 0x18000
	s_add_i32 s78, 0, 0x1c000
	v_add_u32_e32 v142, s9, v177
	v_add_u32_e32 v180, s78, v177
	ds_read_b128 v[130:133], v142
	ds_read_b128 v[134:137], v142 offset:1024
	ds_read_b128 v[138:141], v142 offset:2048
	ds_read_b128 v[142:145], v142 offset:3072
	ds_read_b128 v[164:167], v180
	ds_read_b128 v[168:171], v180 offset:1024
	ds_read_b128 v[172:175], v180 offset:2048
	ds_read_b128 v[180:183], v180 offset:3072
	s_add_u32 s72, s72, 0x40000
	s_addc_u32 s73, s73, 0
	s_mov_b32 m0, s44
	v_lshl_add_u64 v[220:221], s[72:73], 0, v[146:147]
	ds_read_b128 v[184:187], v179 offset:32768
	ds_read_b128 v[188:191], v179 offset:33792
	ds_read_b128 v[192:195], v179 offset:34816
	ds_read_b128 v[196:199], v179 offset:35840
	ds_read_b128 v[200:203], v179 offset:36864
	ds_read_b128 v[204:207], v179 offset:37888
	ds_read_b128 v[208:211], v179 offset:38912
	ds_read_b128 v[212:215], v179 offset:39936
	global_load_lds_dwordx4 v[220:221], off
	s_mov_b32 m0, s45
	v_lshl_add_u64 v[220:221], s[72:73], 0, v[156:157]
	global_load_lds_dwordx4 v[220:221], off
	s_waitcnt vmcnt(8)
	s_waitcnt lgkmcnt(0)
	s_barrier
	s_setprio 1
	v_mfma_f32_16x16x32_bf16 v[126:129], v[130:133], v[184:187], v[126:129]
	v_mfma_f32_16x16x32_bf16 v[122:125], v[138:141], v[184:187], v[122:125]
	v_mfma_f32_16x16x32_bf16 v[106:109], v[138:141], v[192:195], v[106:109]
	v_mfma_f32_16x16x32_bf16 v[110:113], v[130:133], v[192:195], v[110:113]
	v_mfma_f32_16x16x32_bf16 v[94:97], v[130:133], v[200:203], v[94:97]
	v_mfma_f32_16x16x32_bf16 v[90:93], v[138:141], v[200:203], v[90:93]
	v_mfma_f32_16x16x32_bf16 v[74:77], v[138:141], v[208:211], v[74:77]
	v_mfma_f32_16x16x32_bf16 v[78:81], v[130:133], v[208:211], v[78:81]
	v_mfma_f32_16x16x32_bf16 v[126:129], v[134:137], v[188:191], v[126:129]
	v_mfma_f32_16x16x32_bf16 v[122:125], v[142:145], v[188:191], v[122:125]
	v_mfma_f32_16x16x32_bf16 v[106:109], v[142:145], v[196:199], v[106:109]
	v_mfma_f32_16x16x32_bf16 v[110:113], v[134:137], v[196:199], v[110:113]
	v_mfma_f32_16x16x32_bf16 v[94:97], v[134:137], v[204:207], v[94:97]
	v_mfma_f32_16x16x32_bf16 v[90:93], v[142:145], v[204:207], v[90:93]
	v_mfma_f32_16x16x32_bf16 v[74:77], v[142:145], v[212:215], v[74:77]
	v_mfma_f32_16x16x32_bf16 v[78:81], v[134:137], v[212:215], v[78:81]
	v_mfma_f32_16x16x32_bf16 v[118:121], v[164:167], v[184:187], v[118:121]
	v_mfma_f32_16x16x32_bf16 v[114:117], v[172:175], v[184:187], v[114:117]
	v_mfma_f32_16x16x32_bf16 v[98:101], v[172:175], v[192:195], v[98:101]
	v_mfma_f32_16x16x32_bf16 v[102:105], v[164:167], v[192:195], v[102:105]
	v_mfma_f32_16x16x32_bf16 v[86:89], v[164:167], v[200:203], v[86:89]
	v_mfma_f32_16x16x32_bf16 v[82:85], v[172:175], v[200:203], v[82:85]
	v_mfma_f32_16x16x32_bf16 v[66:69], v[172:175], v[208:211], v[66:69]
	v_mfma_f32_16x16x32_bf16 v[70:73], v[164:167], v[208:211], v[70:73]
	v_mfma_f32_16x16x32_bf16 v[118:121], v[168:171], v[188:191], v[118:121]
	v_mfma_f32_16x16x32_bf16 v[114:117], v[180:183], v[188:191], v[114:117]
	v_mfma_f32_16x16x32_bf16 v[98:101], v[180:183], v[196:199], v[98:101]
	v_mfma_f32_16x16x32_bf16 v[102:105], v[168:171], v[196:199], v[102:105]
	v_mfma_f32_16x16x32_bf16 v[86:89], v[168:171], v[204:207], v[86:89]
	v_mfma_f32_16x16x32_bf16 v[82:85], v[180:183], v[204:207], v[82:85]
	v_mfma_f32_16x16x32_bf16 v[66:69], v[180:183], v[212:215], v[66:69]
	v_mfma_f32_16x16x32_bf16 v[70:73], v[168:171], v[212:215], v[70:73]
	s_setprio 0
	s_barrier
	s_add_i32 s9, s9, s41
	v_lshl_add_u64 v[148:149], v[148:149], 0, s[70:71]
	s_mov_b32 m0, s9
	ds_read_b128 v[184:187], v179 offset:49152
	ds_read_b128 v[188:191], v179 offset:50176
	ds_read_b128 v[192:195], v179 offset:51200
	ds_read_b128 v[196:199], v179 offset:52224
	ds_read_b128 v[200:203], v179 offset:53248
	ds_read_b128 v[204:207], v179 offset:54272
	ds_read_b128 v[208:211], v179 offset:55296
	ds_read_b128 v[212:215], v179 offset:56320
	global_load_lds_dwordx4 v[148:149], off
	s_add_i32 m0, s9, 0x2000
	s_add_u32 s26, s26, 0x40080
	v_lshl_add_u64 v[148:149], v[150:151], 0, s[70:71]
	s_addc_u32 s27, s27, 0
	s_add_i32 s9, s78, s41
	global_load_lds_dwordx4 v[148:149], off
	s_mov_b32 m0, s9
	v_lshl_add_u64 v[148:149], s[26:27], 0, v[0:1]
	global_load_lds_dwordx4 v[148:149], off
	s_add_i32 m0, s9, 0x2000
	v_lshl_add_u64 v[148:149], s[26:27], 0, v[158:159]
	global_load_lds_dwordx4 v[148:149], off
	s_mov_b32 m0, s50
	v_lshl_add_u64 v[148:149], v[216:217], 0, s[70:71]
	global_load_lds_dwordx4 v[148:149], off
	s_mov_b32 m0, s51
	v_lshl_add_u64 v[148:149], v[218:219], 0, s[70:71]
	global_load_lds_dwordx4 v[148:149], off
	s_waitcnt vmcnt(8)
	s_waitcnt lgkmcnt(0)
	s_barrier
	s_setprio 1
	v_mfma_f32_16x16x32_bf16 v[62:65], v[130:133], v[184:187], v[62:65]
	v_mfma_f32_16x16x32_bf16 v[58:61], v[138:141], v[184:187], v[58:61]
	v_mfma_f32_16x16x32_bf16 v[42:45], v[138:141], v[192:195], v[42:45]
	v_mfma_f32_16x16x32_bf16 v[46:49], v[130:133], v[192:195], v[46:49]
	v_mfma_f32_16x16x32_bf16 v[30:33], v[130:133], v[200:203], v[30:33]
	v_mfma_f32_16x16x32_bf16 v[26:29], v[138:141], v[200:203], v[26:29]
	v_mfma_f32_16x16x32_bf16 v[10:13], v[138:141], v[208:211], v[10:13]
	v_mfma_f32_16x16x32_bf16 v[14:17], v[130:133], v[208:211], v[14:17]
	v_mfma_f32_16x16x32_bf16 v[62:65], v[134:137], v[188:191], v[62:65]
	v_mfma_f32_16x16x32_bf16 v[58:61], v[142:145], v[188:191], v[58:61]
	v_mfma_f32_16x16x32_bf16 v[42:45], v[142:145], v[196:199], v[42:45]
	v_mfma_f32_16x16x32_bf16 v[46:49], v[134:137], v[196:199], v[46:49]
	v_mfma_f32_16x16x32_bf16 v[30:33], v[134:137], v[204:207], v[30:33]
	v_mfma_f32_16x16x32_bf16 v[26:29], v[142:145], v[204:207], v[26:29]
	v_mfma_f32_16x16x32_bf16 v[10:13], v[142:145], v[212:215], v[10:13]
	v_mfma_f32_16x16x32_bf16 v[14:17], v[134:137], v[212:215], v[14:17]
	v_mfma_f32_16x16x32_bf16 v[54:57], v[164:167], v[184:187], v[54:57]
	v_mfma_f32_16x16x32_bf16 v[50:53], v[172:175], v[184:187], v[50:53]
	v_mfma_f32_16x16x32_bf16 v[34:37], v[172:175], v[192:195], v[34:37]
	v_mfma_f32_16x16x32_bf16 v[38:41], v[164:167], v[192:195], v[38:41]
	v_mfma_f32_16x16x32_bf16 v[22:25], v[164:167], v[200:203], v[22:25]
	v_mfma_f32_16x16x32_bf16 v[18:21], v[172:175], v[200:203], v[18:21]
	v_mfma_f32_16x16x32_bf16 v[2:5], v[172:175], v[208:211], v[2:5]
	v_mfma_f32_16x16x32_bf16 v[6:9], v[164:167], v[208:211], v[6:9]
	v_mfma_f32_16x16x32_bf16 v[54:57], v[168:171], v[188:191], v[54:57]
	v_mfma_f32_16x16x32_bf16 v[50:53], v[180:183], v[188:191], v[50:53]
	v_mfma_f32_16x16x32_bf16 v[34:37], v[180:183], v[196:199], v[34:37]
	v_mfma_f32_16x16x32_bf16 v[38:41], v[168:171], v[196:199], v[38:41]
	v_mfma_f32_16x16x32_bf16 v[22:25], v[168:171], v[204:207], v[22:25]
	v_mfma_f32_16x16x32_bf16 v[18:21], v[180:183], v[204:207], v[18:21]
	v_mfma_f32_16x16x32_bf16 v[2:5], v[180:183], v[212:215], v[2:5]
	v_mfma_f32_16x16x32_bf16 v[6:9], v[168:171], v[212:215], v[6:9]
	s_setprio 0
	s_barrier
	s_add_u32 s60, s60, 0x100
	s_addc_u32 s61, s61, 0
	s_add_u32 s28, s28, 0x100
	s_addc_u32 s29, s29, 0
	s_cmp_ge_u32 s75, s17
	s_mov_b32 s26, s75
	s_cbranch_scc0 .LBB0_701
	s_and_b64 vcc, exec, s[14:15]
	s_cbranch_vccz .LBB0_704

.LBB0_846:
	s_add_u32 s9, s96, 0xfffc0080
	s_addc_u32 s38, s97, -1
	s_add_i32 s78, 0, 0x10000
	s_cmp_eq_u32 s75, 12
	s_cselect_b32 vcc_hi, s25, s38
	s_cselect_b32 vcc_lo, s28, s9
	v_add_u32_e32 v148, s78, v145
	s_cselect_b32 s39, s23, s61
	s_cselect_b32 s38, s29, s53
	s_add_i32 s9, 0, 0x14000
	ds_read_b128 v[140:143], v148
	ds_read_b128 v[156:159], v148 offset:1024
	ds_read_b128 v[160:163], v148 offset:2048
	ds_read_b128 v[164:167], v148 offset:3072
	v_add_u32_e32 v148, s9, v145
	ds_read_b128 v[168:171], v148
	ds_read_b128 v[172:175], v148 offset:1024
	ds_read_b128 v[176:179], v148 offset:2048
	ds_read_b128 v[180:183], v148 offset:3072
	v_lshl_add_u64 v[148:149], s[96:97], 0, v[136:137]
	s_add_i32 m0, s46, 0xc000
	ds_read_b128 v[184:187], v147
	ds_read_b128 v[188:191], v147 offset:1024
	ds_read_b128 v[192:195], v147 offset:2048
	ds_read_b128 v[196:199], v147 offset:3072
	ds_read_b128 v[200:203], v147 offset:4096
	ds_read_b128 v[204:207], v147 offset:5120
	ds_read_b128 v[208:211], v147 offset:6144
	ds_read_b128 v[212:215], v147 offset:7168
	global_load_lds_dwordx4 v[148:149], off
	s_add_i32 m0, s46, 0xe000
	v_lshl_add_u64 v[148:149], s[96:97], 0, v[138:139]
	global_load_lds_dwordx4 v[148:149], off
	s_waitcnt vmcnt(8)
	s_waitcnt lgkmcnt(0)
	s_barrier
	s_setprio 1
	v_mfma_f32_16x16x32_bf16 v[126:129], v[140:143], v[184:187], v[126:129]
	v_mfma_f32_16x16x32_bf16 v[118:121], v[160:163], v[184:187], v[118:121]
	v_mfma_f32_16x16x32_bf16 v[102:105], v[160:163], v[192:195], v[102:105]
	v_mfma_f32_16x16x32_bf16 v[110:113], v[140:143], v[192:195], v[110:113]
	v_mfma_f32_16x16x32_bf16 v[94:97], v[140:143], v[200:203], v[94:97]
	v_mfma_f32_16x16x32_bf16 v[86:89], v[160:163], v[200:203], v[86:89]
	v_mfma_f32_16x16x32_bf16 v[70:73], v[160:163], v[208:211], v[70:73]
	v_mfma_f32_16x16x32_bf16 v[78:81], v[140:143], v[208:211], v[78:81]
	v_mfma_f32_16x16x32_bf16 v[126:129], v[156:159], v[188:191], v[126:129]
	v_mfma_f32_16x16x32_bf16 v[118:121], v[164:167], v[188:191], v[118:121]
	v_mfma_f32_16x16x32_bf16 v[102:105], v[164:167], v[196:199], v[102:105]
	v_mfma_f32_16x16x32_bf16 v[110:113], v[156:159], v[196:199], v[110:113]
	v_mfma_f32_16x16x32_bf16 v[94:97], v[156:159], v[204:207], v[94:97]
	v_mfma_f32_16x16x32_bf16 v[86:89], v[164:167], v[204:207], v[86:89]
	v_mfma_f32_16x16x32_bf16 v[70:73], v[164:167], v[212:215], v[70:73]
	v_mfma_f32_16x16x32_bf16 v[78:81], v[156:159], v[212:215], v[78:81]
	v_mfma_f32_16x16x32_bf16 v[122:125], v[168:171], v[184:187], v[122:125]
	v_mfma_f32_16x16x32_bf16 v[114:117], v[176:179], v[184:187], v[114:117]
	v_mfma_f32_16x16x32_bf16 v[98:101], v[176:179], v[192:195], v[98:101]
	v_mfma_f32_16x16x32_bf16 v[106:109], v[168:171], v[192:195], v[106:109]
	v_mfma_f32_16x16x32_bf16 v[90:93], v[168:171], v[200:203], v[90:93]
	v_mfma_f32_16x16x32_bf16 v[82:85], v[176:179], v[200:203], v[82:85]
	v_mfma_f32_16x16x32_bf16 v[66:69], v[176:179], v[208:211], v[66:69]
	v_mfma_f32_16x16x32_bf16 v[74:77], v[168:171], v[208:211], v[74:77]
	v_mfma_f32_16x16x32_bf16 v[122:125], v[172:175], v[188:191], v[122:125]
	v_mfma_f32_16x16x32_bf16 v[114:117], v[180:183], v[188:191], v[114:117]
	v_mfma_f32_16x16x32_bf16 v[98:101], v[180:183], v[196:199], v[98:101]
	v_mfma_f32_16x16x32_bf16 v[106:109], v[172:175], v[196:199], v[106:109]
	v_mfma_f32_16x16x32_bf16 v[90:93], v[172:175], v[204:207], v[90:93]
	v_mfma_f32_16x16x32_bf16 v[82:85], v[180:183], v[204:207], v[82:85]
	v_mfma_f32_16x16x32_bf16 v[66:69], v[180:183], v[212:215], v[66:69]
	v_mfma_f32_16x16x32_bf16 v[74:77], v[172:175], v[212:215], v[74:77]
	s_setprio 0
	s_barrier
	s_add_i32 s78, s78, s45
	v_lshl_add_u64 v[148:149], s[38:39], 0, v[0:1]
	s_mov_b32 m0, s78
	ds_read_b128 v[184:187], v147 offset:16384
	ds_read_b128 v[188:191], v147 offset:17408
	ds_read_b128 v[192:195], v147 offset:18432
	ds_read_b128 v[196:199], v147 offset:19456
	ds_read_b128 v[200:203], v147 offset:20480
	ds_read_b128 v[204:207], v147 offset:21504
	ds_read_b128 v[208:211], v147 offset:22528
	ds_read_b128 v[212:215], v147 offset:23552
	global_load_lds_dwordx4 v[148:149], off
	s_add_i32 m0, s78, 0x2000
	s_add_u32 s78, s38, 0x40000
	v_lshl_add_u64 v[150:151], s[38:39], 0, v[134:135]
	s_addc_u32 s79, s39, 0
	s_add_i32 s9, s9, s45
	global_load_lds_dwordx4 v[150:151], off
	v_lshl_add_u64 v[216:217], s[78:79], 0, v[0:1]
	s_mov_b32 m0, s9
	v_lshl_add_u64 v[218:219], vcc, 0, v[132:133]
	global_load_lds_dwordx4 v[216:217], off
	s_add_i32 m0, s9, 0x2000
	v_lshl_add_u64 v[216:217], s[78:79], 0, v[134:135]
	global_load_lds_dwordx4 v[216:217], off
	s_mov_b32 m0, s46
	v_lshl_add_u64 v[216:217], vcc, 0, v[130:131]
	global_load_lds_dwordx4 v[216:217], off
	s_mov_b32 m0, s47
	s_nop 0
	global_load_lds_dwordx4 v[218:219], off
	s_waitcnt vmcnt(8)
	s_waitcnt lgkmcnt(0)
	s_barrier
	s_setprio 1
	v_mfma_f32_16x16x32_bf16 v[62:65], v[140:143], v[184:187], v[62:65]
	v_mfma_f32_16x16x32_bf16 v[54:57], v[160:163], v[184:187], v[54:57]
	v_mfma_f32_16x16x32_bf16 v[38:41], v[160:163], v[192:195], v[38:41]
	v_mfma_f32_16x16x32_bf16 v[46:49], v[140:143], v[192:195], v[46:49]
	v_mfma_f32_16x16x32_bf16 v[30:33], v[140:143], v[200:203], v[30:33]
	v_mfma_f32_16x16x32_bf16 v[22:25], v[160:163], v[200:203], v[22:25]
	v_mfma_f32_16x16x32_bf16 v[6:9], v[160:163], v[208:211], v[6:9]
	v_mfma_f32_16x16x32_bf16 v[14:17], v[140:143], v[208:211], v[14:17]
	v_mfma_f32_16x16x32_bf16 v[62:65], v[156:159], v[188:191], v[62:65]
	v_mfma_f32_16x16x32_bf16 v[54:57], v[164:167], v[188:191], v[54:57]
	v_mfma_f32_16x16x32_bf16 v[38:41], v[164:167], v[196:199], v[38:41]
	v_mfma_f32_16x16x32_bf16 v[46:49], v[156:159], v[196:199], v[46:49]
	v_mfma_f32_16x16x32_bf16 v[30:33], v[156:159], v[204:207], v[30:33]
	v_mfma_f32_16x16x32_bf16 v[22:25], v[164:167], v[204:207], v[22:25]
	v_mfma_f32_16x16x32_bf16 v[6:9], v[164:167], v[212:215], v[6:9]
	v_mfma_f32_16x16x32_bf16 v[14:17], v[156:159], v[212:215], v[14:17]
	v_mfma_f32_16x16x32_bf16 v[58:61], v[168:171], v[184:187], v[58:61]
	v_mfma_f32_16x16x32_bf16 v[50:53], v[176:179], v[184:187], v[50:53]
	v_mfma_f32_16x16x32_bf16 v[34:37], v[176:179], v[192:195], v[34:37]
	v_mfma_f32_16x16x32_bf16 v[42:45], v[168:171], v[192:195], v[42:45]
	v_mfma_f32_16x16x32_bf16 v[26:29], v[168:171], v[200:203], v[26:29]
	v_mfma_f32_16x16x32_bf16 v[18:21], v[176:179], v[200:203], v[18:21]
	v_mfma_f32_16x16x32_bf16 v[2:5], v[176:179], v[208:211], v[2:5]
	v_mfma_f32_16x16x32_bf16 v[10:13], v[168:171], v[208:211], v[10:13]
	v_mfma_f32_16x16x32_bf16 v[58:61], v[172:175], v[188:191], v[58:61]
	v_mfma_f32_16x16x32_bf16 v[50:53], v[180:183], v[188:191], v[50:53]
	v_mfma_f32_16x16x32_bf16 v[34:37], v[180:183], v[196:199], v[34:37]
	v_mfma_f32_16x16x32_bf16 v[42:45], v[172:175], v[196:199], v[42:45]
	v_mfma_f32_16x16x32_bf16 v[26:29], v[172:175], v[204:207], v[26:29]
	v_mfma_f32_16x16x32_bf16 v[18:21], v[180:183], v[204:207], v[18:21]
	v_mfma_f32_16x16x32_bf16 v[2:5], v[180:183], v[212:215], v[2:5]
	v_mfma_f32_16x16x32_bf16 v[10:13], v[172:175], v[212:215], v[10:13]
	s_setprio 0
	s_barrier
	s_add_i32 s9, 0, 0x18000
	s_add_i32 s83, 0, 0x1c000
	v_add_u32_e32 v164, s9, v145
	v_add_u32_e32 v180, s83, v145
	ds_read_b128 v[140:143], v164
	ds_read_b128 v[156:159], v164 offset:1024
	ds_read_b128 v[160:163], v164 offset:2048
	ds_read_b128 v[164:167], v164 offset:3072
	ds_read_b128 v[168:171], v180
	ds_read_b128 v[172:175], v180 offset:1024
	ds_read_b128 v[176:179], v180 offset:2048
	ds_read_b128 v[180:183], v180 offset:3072
	s_add_u32 s78, vcc_lo, 0x40000
	s_addc_u32 s79, vcc_hi, 0
	s_mov_b32 m0, s48
	v_lshl_add_u64 v[220:221], s[78:79], 0, v[130:131]
	ds_read_b128 v[184:187], v147 offset:32768
	ds_read_b128 v[188:191], v147 offset:33792
	ds_read_b128 v[192:195], v147 offset:34816
	ds_read_b128 v[196:199], v147 offset:35840
	ds_read_b128 v[200:203], v147 offset:36864
	ds_read_b128 v[204:207], v147 offset:37888
	ds_read_b128 v[208:211], v147 offset:38912
	ds_read_b128 v[212:215], v147 offset:39936
	global_load_lds_dwordx4 v[220:221], off
	s_mov_b32 m0, s49
	v_lshl_add_u64 v[220:221], s[78:79], 0, v[132:133]
	global_load_lds_dwordx4 v[220:221], off
	s_waitcnt vmcnt(8)
	s_waitcnt lgkmcnt(0)
	s_barrier
	s_setprio 1
	v_mfma_f32_16x16x32_bf16 v[126:129], v[140:143], v[184:187], v[126:129]
	v_mfma_f32_16x16x32_bf16 v[118:121], v[160:163], v[184:187], v[118:121]
	v_mfma_f32_16x16x32_bf16 v[102:105], v[160:163], v[192:195], v[102:105]
	v_mfma_f32_16x16x32_bf16 v[110:113], v[140:143], v[192:195], v[110:113]
	v_mfma_f32_16x16x32_bf16 v[94:97], v[140:143], v[200:203], v[94:97]
	v_mfma_f32_16x16x32_bf16 v[86:89], v[160:163], v[200:203], v[86:89]
	v_mfma_f32_16x16x32_bf16 v[70:73], v[160:163], v[208:211], v[70:73]
	v_mfma_f32_16x16x32_bf16 v[78:81], v[140:143], v[208:211], v[78:81]
	v_mfma_f32_16x16x32_bf16 v[126:129], v[156:159], v[188:191], v[126:129]
	v_mfma_f32_16x16x32_bf16 v[118:121], v[164:167], v[188:191], v[118:121]
	v_mfma_f32_16x16x32_bf16 v[102:105], v[164:167], v[196:199], v[102:105]
	v_mfma_f32_16x16x32_bf16 v[110:113], v[156:159], v[196:199], v[110:113]
	v_mfma_f32_16x16x32_bf16 v[94:97], v[156:159], v[204:207], v[94:97]
	v_mfma_f32_16x16x32_bf16 v[86:89], v[164:167], v[204:207], v[86:89]
	v_mfma_f32_16x16x32_bf16 v[70:73], v[164:167], v[212:215], v[70:73]
	v_mfma_f32_16x16x32_bf16 v[78:81], v[156:159], v[212:215], v[78:81]
	v_mfma_f32_16x16x32_bf16 v[122:125], v[168:171], v[184:187], v[122:125]
	v_mfma_f32_16x16x32_bf16 v[114:117], v[176:179], v[184:187], v[114:117]
	v_mfma_f32_16x16x32_bf16 v[98:101], v[176:179], v[192:195], v[98:101]
	v_mfma_f32_16x16x32_bf16 v[106:109], v[168:171], v[192:195], v[106:109]
	v_mfma_f32_16x16x32_bf16 v[90:93], v[168:171], v[200:203], v[90:93]
	v_mfma_f32_16x16x32_bf16 v[82:85], v[176:179], v[200:203], v[82:85]
	v_mfma_f32_16x16x32_bf16 v[66:69], v[176:179], v[208:211], v[66:69]
	v_mfma_f32_16x16x32_bf16 v[74:77], v[168:171], v[208:211], v[74:77]
	v_mfma_f32_16x16x32_bf16 v[122:125], v[172:175], v[188:191], v[122:125]
	v_mfma_f32_16x16x32_bf16 v[114:117], v[180:183], v[188:191], v[114:117]
	v_mfma_f32_16x16x32_bf16 v[98:101], v[180:183], v[196:199], v[98:101]
	v_mfma_f32_16x16x32_bf16 v[106:109], v[172:175], v[196:199], v[106:109]
	v_mfma_f32_16x16x32_bf16 v[90:93], v[172:175], v[204:207], v[90:93]
	v_mfma_f32_16x16x32_bf16 v[82:85], v[180:183], v[204:207], v[82:85]
	v_mfma_f32_16x16x32_bf16 v[66:69], v[180:183], v[212:215], v[66:69]
	v_mfma_f32_16x16x32_bf16 v[74:77], v[172:175], v[212:215], v[74:77]
	s_setprio 0
	s_barrier
	s_add_i32 s9, s9, s45
	v_lshl_add_u64 v[148:149], v[148:149], 0, s[70:71]
	s_mov_b32 m0, s9
	ds_read_b128 v[184:187], v147 offset:49152
	ds_read_b128 v[188:191], v147 offset:50176
	ds_read_b128 v[192:195], v147 offset:51200
	ds_read_b128 v[196:199], v147 offset:52224
	ds_read_b128 v[200:203], v147 offset:53248
	ds_read_b128 v[204:207], v147 offset:54272
	ds_read_b128 v[208:211], v147 offset:55296
	ds_read_b128 v[212:215], v147 offset:56320
	global_load_lds_dwordx4 v[148:149], off
	s_add_i32 m0, s9, 0x2000
	s_add_u32 s38, s38, 0x40080
	v_lshl_add_u64 v[148:149], v[150:151], 0, s[70:71]
	s_addc_u32 s39, s39, 0
	s_add_i32 s9, s83, s45
	global_load_lds_dwordx4 v[148:149], off
	s_mov_b32 m0, s9
	v_lshl_add_u64 v[148:149], s[38:39], 0, v[0:1]
	global_load_lds_dwordx4 v[148:149], off
	s_add_i32 m0, s9, 0x2000
	v_lshl_add_u64 v[148:149], s[38:39], 0, v[134:135]
	global_load_lds_dwordx4 v[148:149], off
	s_mov_b32 m0, s50
	v_lshl_add_u64 v[148:149], v[216:217], 0, s[70:71]
	global_load_lds_dwordx4 v[148:149], off
	s_mov_b32 m0, s51
	v_lshl_add_u64 v[148:149], v[218:219], 0, s[70:71]
	global_load_lds_dwordx4 v[148:149], off
	s_waitcnt vmcnt(8)
	s_waitcnt lgkmcnt(0)
	s_barrier
	s_setprio 1
	v_mfma_f32_16x16x32_bf16 v[62:65], v[140:143], v[184:187], v[62:65]
	v_mfma_f32_16x16x32_bf16 v[54:57], v[160:163], v[184:187], v[54:57]
	v_mfma_f32_16x16x32_bf16 v[38:41], v[160:163], v[192:195], v[38:41]
	v_mfma_f32_16x16x32_bf16 v[46:49], v[140:143], v[192:195], v[46:49]
	v_mfma_f32_16x16x32_bf16 v[30:33], v[140:143], v[200:203], v[30:33]
	v_mfma_f32_16x16x32_bf16 v[22:25], v[160:163], v[200:203], v[22:25]
	v_mfma_f32_16x16x32_bf16 v[6:9], v[160:163], v[208:211], v[6:9]
	v_mfma_f32_16x16x32_bf16 v[14:17], v[140:143], v[208:211], v[14:17]
	v_mfma_f32_16x16x32_bf16 v[62:65], v[156:159], v[188:191], v[62:65]
	v_mfma_f32_16x16x32_bf16 v[54:57], v[164:167], v[188:191], v[54:57]
	v_mfma_f32_16x16x32_bf16 v[38:41], v[164:167], v[196:199], v[38:41]
	v_mfma_f32_16x16x32_bf16 v[46:49], v[156:159], v[196:199], v[46:49]
	v_mfma_f32_16x16x32_bf16 v[30:33], v[156:159], v[204:207], v[30:33]
	v_mfma_f32_16x16x32_bf16 v[22:25], v[164:167], v[204:207], v[22:25]
	v_mfma_f32_16x16x32_bf16 v[6:9], v[164:167], v[212:215], v[6:9]
	v_mfma_f32_16x16x32_bf16 v[14:17], v[156:159], v[212:215], v[14:17]
	v_mfma_f32_16x16x32_bf16 v[58:61], v[168:171], v[184:187], v[58:61]
	v_mfma_f32_16x16x32_bf16 v[50:53], v[176:179], v[184:187], v[50:53]
	v_mfma_f32_16x16x32_bf16 v[34:37], v[176:179], v[192:195], v[34:37]
	v_mfma_f32_16x16x32_bf16 v[42:45], v[168:171], v[192:195], v[42:45]
	v_mfma_f32_16x16x32_bf16 v[26:29], v[168:171], v[200:203], v[26:29]
	v_mfma_f32_16x16x32_bf16 v[18:21], v[176:179], v[200:203], v[18:21]
	v_mfma_f32_16x16x32_bf16 v[2:5], v[176:179], v[208:211], v[2:5]
	v_mfma_f32_16x16x32_bf16 v[10:13], v[168:171], v[208:211], v[10:13]
	v_mfma_f32_16x16x32_bf16 v[58:61], v[172:175], v[188:191], v[58:61]
	v_mfma_f32_16x16x32_bf16 v[50:53], v[180:183], v[188:191], v[50:53]
	v_mfma_f32_16x16x32_bf16 v[34:37], v[180:183], v[196:199], v[34:37]
	v_mfma_f32_16x16x32_bf16 v[42:45], v[172:175], v[196:199], v[42:45]
	v_mfma_f32_16x16x32_bf16 v[26:29], v[172:175], v[204:207], v[26:29]
	v_mfma_f32_16x16x32_bf16 v[18:21], v[180:183], v[204:207], v[18:21]
	v_mfma_f32_16x16x32_bf16 v[2:5], v[180:183], v[212:215], v[2:5]
	v_mfma_f32_16x16x32_bf16 v[10:13], v[172:175], v[212:215], v[10:13]
	s_setprio 0
	s_barrier
	s_add_i32 s75, s75, 2
	s_add_u32 s96, s96, 0x100
	s_addc_u32 s97, s97, 0
	s_add_u32 s53, s53, 0x100
	s_addc_u32 s61, s61, 0
	s_cmp_gt_u32 s75, 13
	s_cbranch_scc0 .LBB0_846
	s_and_b64 vcc, exec, s[14:15]
	s_cbranch_vccz .LBB0_849
	s_barrier

.LBB0_950:
	s_add_i32 s9, s26, 2
	s_add_u32 s60, s38, 0x100
	s_addc_u32 s61, s39, 0
	s_add_i32 s78, 0, 0x10000
	s_cmp_eq_u32 s29, s26
	s_cselect_b32 s73, s25, s61
	s_cselect_b32 s72, s24, s60
	s_cselect_b32 s27, s37, vcc_hi
	s_cselect_b32 s26, s36, vcc_lo
	s_add_i32 s79, 0, 0x14000
	v_add_u32_e32 v156, s78, v177
	v_add_u32_e32 v172, s79, v177
	ds_read_b128 v[140:143], v156
	ds_read_b128 v[144:147], v156 offset:1024
	ds_read_b128 v[148:151], v156 offset:2048
	ds_read_b128 v[156:159], v156 offset:3072
	ds_read_b128 v[160:163], v172
	ds_read_b128 v[164:167], v172 offset:1024
	ds_read_b128 v[168:171], v172 offset:2048
	ds_read_b128 v[172:175], v172 offset:3072
	v_lshl_add_u64 v[212:213], s[38:39], 0, v[136:137]
	s_add_i32 m0, s50, 0xc000
	ds_read_b128 v[180:183], v179
	ds_read_b128 v[184:187], v179 offset:1024
	ds_read_b128 v[188:191], v179 offset:2048
	ds_read_b128 v[192:195], v179 offset:3072
	ds_read_b128 v[196:199], v179 offset:4096
	ds_read_b128 v[200:203], v179 offset:5120
	ds_read_b128 v[204:207], v179 offset:6144
	ds_read_b128 v[208:211], v179 offset:7168
	global_load_lds_dwordx4 v[212:213], off
	s_add_i32 m0, s50, 0xe000
	v_lshl_add_u64 v[212:213], s[38:39], 0, v[138:139]
	global_load_lds_dwordx4 v[212:213], off
	s_waitcnt vmcnt(8)
	s_waitcnt lgkmcnt(0)
	s_barrier
	s_setprio 1
	v_mfma_f32_16x16x32_bf16 v[126:129], v[140:143], v[180:183], v[126:129]
	v_mfma_f32_16x16x32_bf16 v[122:125], v[148:151], v[180:183], v[122:125]
	v_mfma_f32_16x16x32_bf16 v[106:109], v[148:151], v[188:191], v[106:109]
	v_mfma_f32_16x16x32_bf16 v[110:113], v[140:143], v[188:191], v[110:113]
	v_mfma_f32_16x16x32_bf16 v[94:97], v[140:143], v[196:199], v[94:97]
	v_mfma_f32_16x16x32_bf16 v[90:93], v[148:151], v[196:199], v[90:93]
	v_mfma_f32_16x16x32_bf16 v[74:77], v[148:151], v[204:207], v[74:77]
	v_mfma_f32_16x16x32_bf16 v[78:81], v[140:143], v[204:207], v[78:81]
	v_mfma_f32_16x16x32_bf16 v[126:129], v[144:147], v[184:187], v[126:129]
	v_mfma_f32_16x16x32_bf16 v[122:125], v[156:159], v[184:187], v[122:125]
	v_mfma_f32_16x16x32_bf16 v[106:109], v[156:159], v[192:195], v[106:109]
	v_mfma_f32_16x16x32_bf16 v[110:113], v[144:147], v[192:195], v[110:113]
	v_mfma_f32_16x16x32_bf16 v[94:97], v[144:147], v[200:203], v[94:97]
	v_mfma_f32_16x16x32_bf16 v[90:93], v[156:159], v[200:203], v[90:93]
	v_mfma_f32_16x16x32_bf16 v[74:77], v[156:159], v[208:211], v[74:77]
	v_mfma_f32_16x16x32_bf16 v[78:81], v[144:147], v[208:211], v[78:81]
	v_mfma_f32_16x16x32_bf16 v[118:121], v[160:163], v[180:183], v[118:121]
	v_mfma_f32_16x16x32_bf16 v[114:117], v[168:171], v[180:183], v[114:117]
	v_mfma_f32_16x16x32_bf16 v[98:101], v[168:171], v[188:191], v[98:101]
	v_mfma_f32_16x16x32_bf16 v[102:105], v[160:163], v[188:191], v[102:105]
	v_mfma_f32_16x16x32_bf16 v[86:89], v[160:163], v[196:199], v[86:89]
	v_mfma_f32_16x16x32_bf16 v[82:85], v[168:171], v[196:199], v[82:85]
	v_mfma_f32_16x16x32_bf16 v[66:69], v[168:171], v[204:207], v[66:69]
	v_mfma_f32_16x16x32_bf16 v[70:73], v[160:163], v[204:207], v[70:73]
	v_mfma_f32_16x16x32_bf16 v[118:121], v[164:167], v[184:187], v[118:121]
	v_mfma_f32_16x16x32_bf16 v[114:117], v[172:175], v[184:187], v[114:117]
	v_mfma_f32_16x16x32_bf16 v[98:101], v[172:175], v[192:195], v[98:101]
	v_mfma_f32_16x16x32_bf16 v[102:105], v[164:167], v[192:195], v[102:105]
	v_mfma_f32_16x16x32_bf16 v[86:89], v[164:167], v[200:203], v[86:89]
	v_mfma_f32_16x16x32_bf16 v[82:85], v[172:175], v[200:203], v[82:85]
	v_mfma_f32_16x16x32_bf16 v[66:69], v[172:175], v[208:211], v[66:69]
	v_mfma_f32_16x16x32_bf16 v[70:73], v[164:167], v[208:211], v[70:73]
	s_setprio 0
	s_barrier
	s_add_i32 s38, s78, s49
	v_lshl_add_u64 v[212:213], s[26:27], 0, v[0:1]
	s_mov_b32 m0, s38
	ds_read_b128 v[180:183], v179 offset:16384
	ds_read_b128 v[184:187], v179 offset:17408
	ds_read_b128 v[188:191], v179 offset:18432
	ds_read_b128 v[192:195], v179 offset:19456
	ds_read_b128 v[196:199], v179 offset:20480
	ds_read_b128 v[200:203], v179 offset:21504
	ds_read_b128 v[204:207], v179 offset:22528
	ds_read_b128 v[208:211], v179 offset:23552
	global_load_lds_dwordx4 v[212:213], off
	s_add_i32 m0, s38, 0x2000
	s_add_u32 s38, s26, 0xb0000
	v_lshl_add_u64 v[214:215], s[26:27], 0, v[134:135]
	s_addc_u32 s39, s27, 0
	s_add_i32 s78, s79, s49
	global_load_lds_dwordx4 v[214:215], off
	v_lshl_add_u64 v[216:217], s[38:39], 0, v[0:1]
	s_mov_b32 m0, s78
	v_lshl_add_u64 v[218:219], s[72:73], 0, v[132:133]
	global_load_lds_dwordx4 v[216:217], off
	s_add_i32 m0, s78, 0x2000
	v_lshl_add_u64 v[216:217], s[38:39], 0, v[134:135]
	global_load_lds_dwordx4 v[216:217], off
	s_mov_b32 m0, s50
	v_lshl_add_u64 v[216:217], s[72:73], 0, v[130:131]
	global_load_lds_dwordx4 v[216:217], off
	s_mov_b32 m0, s51
	s_nop 0
	global_load_lds_dwordx4 v[218:219], off
	s_waitcnt vmcnt(8)
	s_waitcnt lgkmcnt(0)
	s_barrier
	s_setprio 1
	v_mfma_f32_16x16x32_bf16 v[62:65], v[140:143], v[180:183], v[62:65]
	v_mfma_f32_16x16x32_bf16 v[58:61], v[148:151], v[180:183], v[58:61]
	v_mfma_f32_16x16x32_bf16 v[42:45], v[148:151], v[188:191], v[42:45]
	v_mfma_f32_16x16x32_bf16 v[46:49], v[140:143], v[188:191], v[46:49]
	v_mfma_f32_16x16x32_bf16 v[30:33], v[140:143], v[196:199], v[30:33]
	v_mfma_f32_16x16x32_bf16 v[26:29], v[148:151], v[196:199], v[26:29]
	v_mfma_f32_16x16x32_bf16 v[10:13], v[148:151], v[204:207], v[10:13]
	v_mfma_f32_16x16x32_bf16 v[14:17], v[140:143], v[204:207], v[14:17]
	v_mfma_f32_16x16x32_bf16 v[62:65], v[144:147], v[184:187], v[62:65]
	v_mfma_f32_16x16x32_bf16 v[58:61], v[156:159], v[184:187], v[58:61]
	v_mfma_f32_16x16x32_bf16 v[42:45], v[156:159], v[192:195], v[42:45]
	v_mfma_f32_16x16x32_bf16 v[46:49], v[144:147], v[192:195], v[46:49]
	v_mfma_f32_16x16x32_bf16 v[30:33], v[144:147], v[200:203], v[30:33]
	v_mfma_f32_16x16x32_bf16 v[26:29], v[156:159], v[200:203], v[26:29]
	v_mfma_f32_16x16x32_bf16 v[10:13], v[156:159], v[208:211], v[10:13]
	v_mfma_f32_16x16x32_bf16 v[14:17], v[144:147], v[208:211], v[14:17]
	v_mfma_f32_16x16x32_bf16 v[54:57], v[160:163], v[180:183], v[54:57]
	v_mfma_f32_16x16x32_bf16 v[50:53], v[168:171], v[180:183], v[50:53]
	v_mfma_f32_16x16x32_bf16 v[34:37], v[168:171], v[188:191], v[34:37]
	v_mfma_f32_16x16x32_bf16 v[38:41], v[160:163], v[188:191], v[38:41]
	v_mfma_f32_16x16x32_bf16 v[22:25], v[160:163], v[196:199], v[22:25]
	v_mfma_f32_16x16x32_bf16 v[18:21], v[168:171], v[196:199], v[18:21]
	v_mfma_f32_16x16x32_bf16 v[2:5], v[168:171], v[204:207], v[2:5]
	v_mfma_f32_16x16x32_bf16 v[6:9], v[160:163], v[204:207], v[6:9]
	v_mfma_f32_16x16x32_bf16 v[54:57], v[164:167], v[184:187], v[54:57]
	v_mfma_f32_16x16x32_bf16 v[50:53], v[172:175], v[184:187], v[50:53]
	v_mfma_f32_16x16x32_bf16 v[34:37], v[172:175], v[192:195], v[34:37]
	v_mfma_f32_16x16x32_bf16 v[38:41], v[164:167], v[192:195], v[38:41]
	v_mfma_f32_16x16x32_bf16 v[22:25], v[164:167], v[200:203], v[22:25]
	v_mfma_f32_16x16x32_bf16 v[18:21], v[172:175], v[200:203], v[18:21]
	v_mfma_f32_16x16x32_bf16 v[2:5], v[172:175], v[208:211], v[2:5]
	v_mfma_f32_16x16x32_bf16 v[6:9], v[164:167], v[208:211], v[6:9]
	s_setprio 0
	s_barrier
	s_add_i32 s78, 0, 0x18000
	s_add_i32 s79, 0, 0x1c000
	v_add_u32_e32 v156, s78, v177
	v_add_u32_e32 v172, s79, v177
	ds_read_b128 v[140:143], v156
	ds_read_b128 v[144:147], v156 offset:1024
	ds_read_b128 v[148:151], v156 offset:2048
	ds_read_b128 v[156:159], v156 offset:3072
	ds_read_b128 v[160:163], v172
	ds_read_b128 v[164:167], v172 offset:1024
	ds_read_b128 v[168:171], v172 offset:2048
	ds_read_b128 v[172:175], v172 offset:3072
	s_add_u32 s38, s72, 0xb0000
	s_addc_u32 s39, s73, 0
	s_mov_b32 m0, s52
	v_lshl_add_u64 v[220:221], s[38:39], 0, v[130:131]
	ds_read_b128 v[180:183], v179 offset:32768
	ds_read_b128 v[184:187], v179 offset:33792
	ds_read_b128 v[188:191], v179 offset:34816
	ds_read_b128 v[192:195], v179 offset:35840
	ds_read_b128 v[196:199], v179 offset:36864
	ds_read_b128 v[200:203], v179 offset:37888
	ds_read_b128 v[204:207], v179 offset:38912
	ds_read_b128 v[208:211], v179 offset:39936
	global_load_lds_dwordx4 v[220:221], off
	s_mov_b32 m0, s53
	v_lshl_add_u64 v[220:221], s[38:39], 0, v[132:133]
	global_load_lds_dwordx4 v[220:221], off
	s_waitcnt vmcnt(8)
	s_waitcnt lgkmcnt(0)
	s_barrier
	s_setprio 1
	v_mfma_f32_16x16x32_bf16 v[126:129], v[140:143], v[180:183], v[126:129]
	v_mfma_f32_16x16x32_bf16 v[122:125], v[148:151], v[180:183], v[122:125]
	v_mfma_f32_16x16x32_bf16 v[106:109], v[148:151], v[188:191], v[106:109]
	v_mfma_f32_16x16x32_bf16 v[110:113], v[140:143], v[188:191], v[110:113]
	v_mfma_f32_16x16x32_bf16 v[94:97], v[140:143], v[196:199], v[94:97]
	v_mfma_f32_16x16x32_bf16 v[90:93], v[148:151], v[196:199], v[90:93]
	v_mfma_f32_16x16x32_bf16 v[74:77], v[148:151], v[204:207], v[74:77]
	v_mfma_f32_16x16x32_bf16 v[78:81], v[140:143], v[204:207], v[78:81]
	v_mfma_f32_16x16x32_bf16 v[126:129], v[144:147], v[184:187], v[126:129]
	v_mfma_f32_16x16x32_bf16 v[122:125], v[156:159], v[184:187], v[122:125]
	v_mfma_f32_16x16x32_bf16 v[106:109], v[156:159], v[192:195], v[106:109]
	v_mfma_f32_16x16x32_bf16 v[110:113], v[144:147], v[192:195], v[110:113]
	v_mfma_f32_16x16x32_bf16 v[94:97], v[144:147], v[200:203], v[94:97]
	v_mfma_f32_16x16x32_bf16 v[90:93], v[156:159], v[200:203], v[90:93]
	v_mfma_f32_16x16x32_bf16 v[74:77], v[156:159], v[208:211], v[74:77]
	v_mfma_f32_16x16x32_bf16 v[78:81], v[144:147], v[208:211], v[78:81]
	v_mfma_f32_16x16x32_bf16 v[118:121], v[160:163], v[180:183], v[118:121]
	v_mfma_f32_16x16x32_bf16 v[114:117], v[168:171], v[180:183], v[114:117]
	v_mfma_f32_16x16x32_bf16 v[98:101], v[168:171], v[188:191], v[98:101]
	v_mfma_f32_16x16x32_bf16 v[102:105], v[160:163], v[188:191], v[102:105]
	v_mfma_f32_16x16x32_bf16 v[86:89], v[160:163], v[196:199], v[86:89]
	v_mfma_f32_16x16x32_bf16 v[82:85], v[168:171], v[196:199], v[82:85]
	v_mfma_f32_16x16x32_bf16 v[66:69], v[168:171], v[204:207], v[66:69]
	v_mfma_f32_16x16x32_bf16 v[70:73], v[160:163], v[204:207], v[70:73]
	v_mfma_f32_16x16x32_bf16 v[118:121], v[164:167], v[184:187], v[118:121]
	v_mfma_f32_16x16x32_bf16 v[114:117], v[172:175], v[184:187], v[114:117]
	v_mfma_f32_16x16x32_bf16 v[98:101], v[172:175], v[192:195], v[98:101]
	v_mfma_f32_16x16x32_bf16 v[102:105], v[164:167], v[192:195], v[102:105]
	v_mfma_f32_16x16x32_bf16 v[86:89], v[164:167], v[200:203], v[86:89]
	v_mfma_f32_16x16x32_bf16 v[82:85], v[172:175], v[200:203], v[82:85]
	v_mfma_f32_16x16x32_bf16 v[66:69], v[172:175], v[208:211], v[66:69]
	v_mfma_f32_16x16x32_bf16 v[70:73], v[164:167], v[208:211], v[70:73]
	s_setprio 0
	s_barrier
	s_add_i32 s38, s78, s49
	v_lshl_add_u64 v[212:213], v[212:213], 0, s[70:71]
	s_mov_b32 m0, s38
	ds_read_b128 v[180:183], v179 offset:49152
	ds_read_b128 v[184:187], v179 offset:50176
	ds_read_b128 v[188:191], v179 offset:51200
	ds_read_b128 v[192:195], v179 offset:52224
	ds_read_b128 v[196:199], v179 offset:53248
	ds_read_b128 v[200:203], v179 offset:54272
	ds_read_b128 v[204:207], v179 offset:55296
	ds_read_b128 v[208:211], v179 offset:56320
	global_load_lds_dwordx4 v[212:213], off
	s_add_i32 m0, s38, 0x2000
	s_add_u32 s26, s26, 0xb0080
	v_lshl_add_u64 v[212:213], v[214:215], 0, s[70:71]
	s_addc_u32 s27, s27, 0
	s_add_i32 s38, s79, s49
	global_load_lds_dwordx4 v[212:213], off
	s_mov_b32 m0, s38
	v_lshl_add_u64 v[212:213], s[26:27], 0, v[0:1]
	global_load_lds_dwordx4 v[212:213], off
	s_add_i32 m0, s38, 0x2000
	v_lshl_add_u64 v[212:213], s[26:27], 0, v[134:135]
	global_load_lds_dwordx4 v[212:213], off
	s_mov_b32 m0, s74
	v_lshl_add_u64 v[212:213], v[216:217], 0, s[70:71]
	global_load_lds_dwordx4 v[212:213], off
	s_mov_b32 m0, s75
	v_lshl_add_u64 v[212:213], v[218:219], 0, s[70:71]
	global_load_lds_dwordx4 v[212:213], off
	s_waitcnt vmcnt(8)
	s_waitcnt lgkmcnt(0)
	s_barrier
	s_setprio 1
	v_mfma_f32_16x16x32_bf16 v[62:65], v[140:143], v[180:183], v[62:65]
	v_mfma_f32_16x16x32_bf16 v[58:61], v[148:151], v[180:183], v[58:61]
	v_mfma_f32_16x16x32_bf16 v[42:45], v[148:151], v[188:191], v[42:45]
	v_mfma_f32_16x16x32_bf16 v[46:49], v[140:143], v[188:191], v[46:49]
	v_mfma_f32_16x16x32_bf16 v[30:33], v[140:143], v[196:199], v[30:33]
	v_mfma_f32_16x16x32_bf16 v[26:29], v[148:151], v[196:199], v[26:29]
	v_mfma_f32_16x16x32_bf16 v[10:13], v[148:151], v[204:207], v[10:13]
	v_mfma_f32_16x16x32_bf16 v[14:17], v[140:143], v[204:207], v[14:17]
	v_mfma_f32_16x16x32_bf16 v[62:65], v[144:147], v[184:187], v[62:65]
	v_mfma_f32_16x16x32_bf16 v[58:61], v[156:159], v[184:187], v[58:61]
	v_mfma_f32_16x16x32_bf16 v[42:45], v[156:159], v[192:195], v[42:45]
	v_mfma_f32_16x16x32_bf16 v[46:49], v[144:147], v[192:195], v[46:49]
	v_mfma_f32_16x16x32_bf16 v[30:33], v[144:147], v[200:203], v[30:33]
	v_mfma_f32_16x16x32_bf16 v[26:29], v[156:159], v[200:203], v[26:29]
	v_mfma_f32_16x16x32_bf16 v[10:13], v[156:159], v[208:211], v[10:13]
	v_mfma_f32_16x16x32_bf16 v[14:17], v[144:147], v[208:211], v[14:17]
	v_mfma_f32_16x16x32_bf16 v[54:57], v[160:163], v[180:183], v[54:57]
	v_mfma_f32_16x16x32_bf16 v[50:53], v[168:171], v[180:183], v[50:53]
	v_mfma_f32_16x16x32_bf16 v[34:37], v[168:171], v[188:191], v[34:37]
	v_mfma_f32_16x16x32_bf16 v[38:41], v[160:163], v[188:191], v[38:41]
	v_mfma_f32_16x16x32_bf16 v[22:25], v[160:163], v[196:199], v[22:25]
	v_mfma_f32_16x16x32_bf16 v[18:21], v[168:171], v[196:199], v[18:21]
	v_mfma_f32_16x16x32_bf16 v[2:5], v[168:171], v[204:207], v[2:5]
	v_mfma_f32_16x16x32_bf16 v[6:9], v[160:163], v[204:207], v[6:9]
	v_mfma_f32_16x16x32_bf16 v[54:57], v[164:167], v[184:187], v[54:57]
	v_mfma_f32_16x16x32_bf16 v[50:53], v[172:175], v[184:187], v[50:53]
	v_mfma_f32_16x16x32_bf16 v[34:37], v[172:175], v[192:195], v[34:37]
	v_mfma_f32_16x16x32_bf16 v[38:41], v[164:167], v[192:195], v[38:41]
	v_mfma_f32_16x16x32_bf16 v[22:25], v[164:167], v[200:203], v[22:25]
	v_mfma_f32_16x16x32_bf16 v[18:21], v[172:175], v[200:203], v[18:21]
	v_mfma_f32_16x16x32_bf16 v[2:5], v[172:175], v[208:211], v[2:5]
	v_mfma_f32_16x16x32_bf16 v[6:9], v[164:167], v[208:211], v[6:9]
	s_setprio 0
	s_barrier
	s_add_u32 vcc_lo, vcc_lo, 0x100
	s_addc_u32 vcc_hi, vcc_hi, 0
	s_cmp_ge_u32 s9, s28
	s_mov_b64 s[38:39], s[60:61]
	s_mov_b32 s26, s9
	s_cbranch_scc0 .LBB0_950
	s_and_b64 vcc, exec, s[22:23]
	s_cbranch_vccz .LBB0_953

.LBB0_1000:
	s_add_i32 s9, s26, 2
	s_add_u32 s60, s38, 0x100
	s_addc_u32 s61, s39, 0
	s_add_i32 s78, 0, 0x10000
	s_cmp_eq_u32 s29, s26
	s_cselect_b32 s73, s25, s61
	s_cselect_b32 s72, s24, s60
	v_add_u32_e32 v148, s78, v251
	s_cselect_b32 s27, s37, vcc_hi
	s_cselect_b32 s26, s36, vcc_lo
	s_add_i32 s79, 0, 0x14000
	ds_read_b128 v[140:143], v148
	ds_read_b128 v[144:147], v148 offset:1024
	ds_read_b128 v[156:159], v148 offset:2048
	ds_read_b128 v[160:163], v148 offset:3072
	v_add_u32_e32 v148, s79, v251
	ds_read_b128 v[164:167], v148
	ds_read_b128 v[168:171], v148 offset:1024
	ds_read_b128 v[172:175], v148 offset:2048
	ds_read_b128 v[176:179], v148 offset:3072
	v_lshl_add_u64 v[148:149], s[38:39], 0, v[136:137]
	s_add_i32 m0, s50, 0xc000
	ds_read_b128 v[180:183], v253
	ds_read_b128 v[184:187], v253 offset:1024
	ds_read_b128 v[188:191], v253 offset:2048
	ds_read_b128 v[192:195], v253 offset:3072
	ds_read_b128 v[196:199], v253 offset:4096
	ds_read_b128 v[200:203], v253 offset:5120
	ds_read_b128 v[204:207], v253 offset:6144
	ds_read_b128 v[208:211], v253 offset:7168
	global_load_lds_dwordx4 v[148:149], off
	s_add_i32 m0, s50, 0xe000
	v_lshl_add_u64 v[148:149], s[38:39], 0, v[138:139]
	global_load_lds_dwordx4 v[148:149], off
	s_waitcnt vmcnt(8)
	s_waitcnt lgkmcnt(0)
	s_barrier
	s_setprio 1
	v_mfma_f32_16x16x32_bf16 v[126:129], v[140:143], v[180:183], v[126:129]
	v_mfma_f32_16x16x32_bf16 v[122:125], v[156:159], v[180:183], v[122:125]
	v_mfma_f32_16x16x32_bf16 v[106:109], v[156:159], v[188:191], v[106:109]
	v_mfma_f32_16x16x32_bf16 v[110:113], v[140:143], v[188:191], v[110:113]
	v_mfma_f32_16x16x32_bf16 v[94:97], v[140:143], v[196:199], v[94:97]
	v_mfma_f32_16x16x32_bf16 v[90:93], v[156:159], v[196:199], v[90:93]
	v_mfma_f32_16x16x32_bf16 v[74:77], v[156:159], v[204:207], v[74:77]
	v_mfma_f32_16x16x32_bf16 v[78:81], v[140:143], v[204:207], v[78:81]
	v_mfma_f32_16x16x32_bf16 v[126:129], v[144:147], v[184:187], v[126:129]
	v_mfma_f32_16x16x32_bf16 v[122:125], v[160:163], v[184:187], v[122:125]
	v_mfma_f32_16x16x32_bf16 v[106:109], v[160:163], v[192:195], v[106:109]
	v_mfma_f32_16x16x32_bf16 v[110:113], v[144:147], v[192:195], v[110:113]
	v_mfma_f32_16x16x32_bf16 v[94:97], v[144:147], v[200:203], v[94:97]
	v_mfma_f32_16x16x32_bf16 v[90:93], v[160:163], v[200:203], v[90:93]
	v_mfma_f32_16x16x32_bf16 v[74:77], v[160:163], v[208:211], v[74:77]
	v_mfma_f32_16x16x32_bf16 v[78:81], v[144:147], v[208:211], v[78:81]
	v_mfma_f32_16x16x32_bf16 v[118:121], v[164:167], v[180:183], v[118:121]
	v_mfma_f32_16x16x32_bf16 v[114:117], v[172:175], v[180:183], v[114:117]
	v_mfma_f32_16x16x32_bf16 v[98:101], v[172:175], v[188:191], v[98:101]
	v_mfma_f32_16x16x32_bf16 v[102:105], v[164:167], v[188:191], v[102:105]
	v_mfma_f32_16x16x32_bf16 v[86:89], v[164:167], v[196:199], v[86:89]
	v_mfma_f32_16x16x32_bf16 v[82:85], v[172:175], v[196:199], v[82:85]
	v_mfma_f32_16x16x32_bf16 v[66:69], v[172:175], v[204:207], v[66:69]
	v_mfma_f32_16x16x32_bf16 v[70:73], v[164:167], v[204:207], v[70:73]
	v_mfma_f32_16x16x32_bf16 v[118:121], v[168:171], v[184:187], v[118:121]
	v_mfma_f32_16x16x32_bf16 v[114:117], v[176:179], v[184:187], v[114:117]
	v_mfma_f32_16x16x32_bf16 v[98:101], v[176:179], v[192:195], v[98:101]
	v_mfma_f32_16x16x32_bf16 v[102:105], v[168:171], v[192:195], v[102:105]
	v_mfma_f32_16x16x32_bf16 v[86:89], v[168:171], v[200:203], v[86:89]
	v_mfma_f32_16x16x32_bf16 v[82:85], v[176:179], v[200:203], v[82:85]
	v_mfma_f32_16x16x32_bf16 v[66:69], v[176:179], v[208:211], v[66:69]
	v_mfma_f32_16x16x32_bf16 v[70:73], v[168:171], v[208:211], v[70:73]
	s_setprio 0
	s_barrier
	s_add_i32 s38, s78, s49
	v_lshl_add_u64 v[148:149], s[26:27], 0, v[0:1]
	s_mov_b32 m0, s38
	ds_read_b128 v[180:183], v253 offset:16384
	ds_read_b128 v[184:187], v253 offset:17408
	ds_read_b128 v[188:191], v253 offset:18432
	ds_read_b128 v[192:195], v253 offset:19456
	ds_read_b128 v[196:199], v253 offset:20480
	ds_read_b128 v[200:203], v253 offset:21504
	ds_read_b128 v[204:207], v253 offset:22528
	ds_read_b128 v[208:211], v253 offset:23552
	global_load_lds_dwordx4 v[148:149], off
	s_add_i32 m0, s38, 0x2000
	s_add_u32 s38, s26, 0xb0000
	v_lshl_add_u64 v[150:151], s[26:27], 0, v[134:135]
	s_addc_u32 s39, s27, 0
	s_add_i32 s78, s79, s49
	global_load_lds_dwordx4 v[150:151], off
	v_lshl_add_u64 v[212:213], s[38:39], 0, v[0:1]
	s_mov_b32 m0, s78
	v_lshl_add_u64 v[214:215], s[72:73], 0, v[132:133]
	global_load_lds_dwordx4 v[212:213], off
	s_add_i32 m0, s78, 0x2000
	v_lshl_add_u64 v[212:213], s[38:39], 0, v[134:135]
	global_load_lds_dwordx4 v[212:213], off
	s_mov_b32 m0, s50
	v_lshl_add_u64 v[212:213], s[72:73], 0, v[130:131]
	global_load_lds_dwordx4 v[212:213], off
	s_mov_b32 m0, s51
	s_nop 0
	global_load_lds_dwordx4 v[214:215], off
	s_waitcnt vmcnt(8)
	s_waitcnt lgkmcnt(0)
	s_barrier
	s_setprio 1
	v_mfma_f32_16x16x32_bf16 v[62:65], v[140:143], v[180:183], v[62:65]
	v_mfma_f32_16x16x32_bf16 v[58:61], v[156:159], v[180:183], v[58:61]
	v_mfma_f32_16x16x32_bf16 v[42:45], v[156:159], v[188:191], v[42:45]
	v_mfma_f32_16x16x32_bf16 v[46:49], v[140:143], v[188:191], v[46:49]
	v_mfma_f32_16x16x32_bf16 v[30:33], v[140:143], v[196:199], v[30:33]
	v_mfma_f32_16x16x32_bf16 v[26:29], v[156:159], v[196:199], v[26:29]
	v_mfma_f32_16x16x32_bf16 v[10:13], v[156:159], v[204:207], v[10:13]
	v_mfma_f32_16x16x32_bf16 v[14:17], v[140:143], v[204:207], v[14:17]
	v_mfma_f32_16x16x32_bf16 v[62:65], v[144:147], v[184:187], v[62:65]
	v_mfma_f32_16x16x32_bf16 v[58:61], v[160:163], v[184:187], v[58:61]
	v_mfma_f32_16x16x32_bf16 v[42:45], v[160:163], v[192:195], v[42:45]
	v_mfma_f32_16x16x32_bf16 v[46:49], v[144:147], v[192:195], v[46:49]
	v_mfma_f32_16x16x32_bf16 v[30:33], v[144:147], v[200:203], v[30:33]
	v_mfma_f32_16x16x32_bf16 v[26:29], v[160:163], v[200:203], v[26:29]
	v_mfma_f32_16x16x32_bf16 v[10:13], v[160:163], v[208:211], v[10:13]
	v_mfma_f32_16x16x32_bf16 v[14:17], v[144:147], v[208:211], v[14:17]
	v_mfma_f32_16x16x32_bf16 v[54:57], v[164:167], v[180:183], v[54:57]
	v_mfma_f32_16x16x32_bf16 v[50:53], v[172:175], v[180:183], v[50:53]
	v_mfma_f32_16x16x32_bf16 v[34:37], v[172:175], v[188:191], v[34:37]
	v_mfma_f32_16x16x32_bf16 v[38:41], v[164:167], v[188:191], v[38:41]
	v_mfma_f32_16x16x32_bf16 v[22:25], v[164:167], v[196:199], v[22:25]
	v_mfma_f32_16x16x32_bf16 v[18:21], v[172:175], v[196:199], v[18:21]
	v_mfma_f32_16x16x32_bf16 v[2:5], v[172:175], v[204:207], v[2:5]
	v_mfma_f32_16x16x32_bf16 v[6:9], v[164:167], v[204:207], v[6:9]
	v_mfma_f32_16x16x32_bf16 v[54:57], v[168:171], v[184:187], v[54:57]
	v_mfma_f32_16x16x32_bf16 v[50:53], v[176:179], v[184:187], v[50:53]
	v_mfma_f32_16x16x32_bf16 v[34:37], v[176:179], v[192:195], v[34:37]
	v_mfma_f32_16x16x32_bf16 v[38:41], v[168:171], v[192:195], v[38:41]
	v_mfma_f32_16x16x32_bf16 v[22:25], v[168:171], v[200:203], v[22:25]
	v_mfma_f32_16x16x32_bf16 v[18:21], v[176:179], v[200:203], v[18:21]
	v_mfma_f32_16x16x32_bf16 v[2:5], v[176:179], v[208:211], v[2:5]
	v_mfma_f32_16x16x32_bf16 v[6:9], v[168:171], v[208:211], v[6:9]
	s_setprio 0
	s_barrier
	s_add_i32 s78, 0, 0x18000
	s_add_i32 s79, 0, 0x1c000
	v_add_u32_e32 v160, s78, v251
	v_add_u32_e32 v176, s79, v251
	ds_read_b128 v[140:143], v160
	ds_read_b128 v[144:147], v160 offset:1024
	ds_read_b128 v[156:159], v160 offset:2048
	ds_read_b128 v[160:163], v160 offset:3072
	ds_read_b128 v[164:167], v176
	ds_read_b128 v[168:171], v176 offset:1024
	ds_read_b128 v[172:175], v176 offset:2048
	ds_read_b128 v[176:179], v176 offset:3072
	s_add_u32 s38, s72, 0xb0000
	s_addc_u32 s39, s73, 0
	s_mov_b32 m0, s52
	v_lshl_add_u64 v[216:217], s[38:39], 0, v[130:131]
	ds_read_b128 v[180:183], v253 offset:32768
	ds_read_b128 v[184:187], v253 offset:33792
	ds_read_b128 v[188:191], v253 offset:34816
	ds_read_b128 v[192:195], v253 offset:35840
	ds_read_b128 v[196:199], v253 offset:36864
	ds_read_b128 v[200:203], v253 offset:37888
	ds_read_b128 v[204:207], v253 offset:38912
	ds_read_b128 v[208:211], v253 offset:39936
	global_load_lds_dwordx4 v[216:217], off
	s_mov_b32 m0, s53
	v_lshl_add_u64 v[216:217], s[38:39], 0, v[132:133]
	global_load_lds_dwordx4 v[216:217], off
	s_waitcnt vmcnt(8)
	s_waitcnt lgkmcnt(0)
	s_barrier
	s_setprio 1
	v_mfma_f32_16x16x32_bf16 v[126:129], v[140:143], v[180:183], v[126:129]
	v_mfma_f32_16x16x32_bf16 v[122:125], v[156:159], v[180:183], v[122:125]
	v_mfma_f32_16x16x32_bf16 v[106:109], v[156:159], v[188:191], v[106:109]
	v_mfma_f32_16x16x32_bf16 v[110:113], v[140:143], v[188:191], v[110:113]
	v_mfma_f32_16x16x32_bf16 v[94:97], v[140:143], v[196:199], v[94:97]
	v_mfma_f32_16x16x32_bf16 v[90:93], v[156:159], v[196:199], v[90:93]
	v_mfma_f32_16x16x32_bf16 v[74:77], v[156:159], v[204:207], v[74:77]
	v_mfma_f32_16x16x32_bf16 v[78:81], v[140:143], v[204:207], v[78:81]
	v_mfma_f32_16x16x32_bf16 v[126:129], v[144:147], v[184:187], v[126:129]
	v_mfma_f32_16x16x32_bf16 v[122:125], v[160:163], v[184:187], v[122:125]
	v_mfma_f32_16x16x32_bf16 v[106:109], v[160:163], v[192:195], v[106:109]
	v_mfma_f32_16x16x32_bf16 v[110:113], v[144:147], v[192:195], v[110:113]
	v_mfma_f32_16x16x32_bf16 v[94:97], v[144:147], v[200:203], v[94:97]
	v_mfma_f32_16x16x32_bf16 v[90:93], v[160:163], v[200:203], v[90:93]
	v_mfma_f32_16x16x32_bf16 v[74:77], v[160:163], v[208:211], v[74:77]
	v_mfma_f32_16x16x32_bf16 v[78:81], v[144:147], v[208:211], v[78:81]
	v_mfma_f32_16x16x32_bf16 v[118:121], v[164:167], v[180:183], v[118:121]
	v_mfma_f32_16x16x32_bf16 v[114:117], v[172:175], v[180:183], v[114:117]
	v_mfma_f32_16x16x32_bf16 v[98:101], v[172:175], v[188:191], v[98:101]
	v_mfma_f32_16x16x32_bf16 v[102:105], v[164:167], v[188:191], v[102:105]
	v_mfma_f32_16x16x32_bf16 v[86:89], v[164:167], v[196:199], v[86:89]
	v_mfma_f32_16x16x32_bf16 v[82:85], v[172:175], v[196:199], v[82:85]
	v_mfma_f32_16x16x32_bf16 v[66:69], v[172:175], v[204:207], v[66:69]
	v_mfma_f32_16x16x32_bf16 v[70:73], v[164:167], v[204:207], v[70:73]
	v_mfma_f32_16x16x32_bf16 v[118:121], v[168:171], v[184:187], v[118:121]
	v_mfma_f32_16x16x32_bf16 v[114:117], v[176:179], v[184:187], v[114:117]
	v_mfma_f32_16x16x32_bf16 v[98:101], v[176:179], v[192:195], v[98:101]
	v_mfma_f32_16x16x32_bf16 v[102:105], v[168:171], v[192:195], v[102:105]
	v_mfma_f32_16x16x32_bf16 v[86:89], v[168:171], v[200:203], v[86:89]
	v_mfma_f32_16x16x32_bf16 v[82:85], v[176:179], v[200:203], v[82:85]
	v_mfma_f32_16x16x32_bf16 v[66:69], v[176:179], v[208:211], v[66:69]
	v_mfma_f32_16x16x32_bf16 v[70:73], v[168:171], v[208:211], v[70:73]
	s_setprio 0
	s_barrier
	s_add_i32 s38, s78, s49
	v_lshl_add_u64 v[148:149], v[148:149], 0, s[70:71]
	s_mov_b32 m0, s38
	ds_read_b128 v[180:183], v253 offset:49152
	ds_read_b128 v[184:187], v253 offset:50176
	ds_read_b128 v[188:191], v253 offset:51200
	ds_read_b128 v[192:195], v253 offset:52224
	ds_read_b128 v[196:199], v253 offset:53248
	ds_read_b128 v[200:203], v253 offset:54272
	ds_read_b128 v[204:207], v253 offset:55296
	ds_read_b128 v[208:211], v253 offset:56320
	global_load_lds_dwordx4 v[148:149], off
	s_add_i32 m0, s38, 0x2000
	s_add_u32 s26, s26, 0xb0080
	v_lshl_add_u64 v[148:149], v[150:151], 0, s[70:71]
	s_addc_u32 s27, s27, 0
	s_add_i32 s38, s79, s49
	global_load_lds_dwordx4 v[148:149], off
	s_mov_b32 m0, s38
	v_lshl_add_u64 v[148:149], s[26:27], 0, v[0:1]
	global_load_lds_dwordx4 v[148:149], off
	s_add_i32 m0, s38, 0x2000
	v_lshl_add_u64 v[148:149], s[26:27], 0, v[134:135]
	global_load_lds_dwordx4 v[148:149], off
	s_mov_b32 m0, s74
	v_lshl_add_u64 v[148:149], v[212:213], 0, s[70:71]
	global_load_lds_dwordx4 v[148:149], off
	s_mov_b32 m0, s75
	v_lshl_add_u64 v[148:149], v[214:215], 0, s[70:71]
	global_load_lds_dwordx4 v[148:149], off
	s_waitcnt vmcnt(8)
	s_waitcnt lgkmcnt(0)
	s_barrier
	s_setprio 1
	v_mfma_f32_16x16x32_bf16 v[62:65], v[140:143], v[180:183], v[62:65]
	v_mfma_f32_16x16x32_bf16 v[58:61], v[156:159], v[180:183], v[58:61]
	v_mfma_f32_16x16x32_bf16 v[42:45], v[156:159], v[188:191], v[42:45]
	v_mfma_f32_16x16x32_bf16 v[46:49], v[140:143], v[188:191], v[46:49]
	v_mfma_f32_16x16x32_bf16 v[30:33], v[140:143], v[196:199], v[30:33]
	v_mfma_f32_16x16x32_bf16 v[26:29], v[156:159], v[196:199], v[26:29]
	v_mfma_f32_16x16x32_bf16 v[10:13], v[156:159], v[204:207], v[10:13]
	v_mfma_f32_16x16x32_bf16 v[14:17], v[140:143], v[204:207], v[14:17]
	v_mfma_f32_16x16x32_bf16 v[62:65], v[144:147], v[184:187], v[62:65]
	v_mfma_f32_16x16x32_bf16 v[58:61], v[160:163], v[184:187], v[58:61]
	v_mfma_f32_16x16x32_bf16 v[42:45], v[160:163], v[192:195], v[42:45]
	v_mfma_f32_16x16x32_bf16 v[46:49], v[144:147], v[192:195], v[46:49]
	v_mfma_f32_16x16x32_bf16 v[30:33], v[144:147], v[200:203], v[30:33]
	v_mfma_f32_16x16x32_bf16 v[26:29], v[160:163], v[200:203], v[26:29]
	v_mfma_f32_16x16x32_bf16 v[10:13], v[160:163], v[208:211], v[10:13]
	v_mfma_f32_16x16x32_bf16 v[14:17], v[144:147], v[208:211], v[14:17]
	v_mfma_f32_16x16x32_bf16 v[54:57], v[164:167], v[180:183], v[54:57]
	v_mfma_f32_16x16x32_bf16 v[50:53], v[172:175], v[180:183], v[50:53]
	v_mfma_f32_16x16x32_bf16 v[34:37], v[172:175], v[188:191], v[34:37]
	v_mfma_f32_16x16x32_bf16 v[38:41], v[164:167], v[188:191], v[38:41]
	v_mfma_f32_16x16x32_bf16 v[22:25], v[164:167], v[196:199], v[22:25]
	v_mfma_f32_16x16x32_bf16 v[18:21], v[172:175], v[196:199], v[18:21]
	v_mfma_f32_16x16x32_bf16 v[2:5], v[172:175], v[204:207], v[2:5]
	v_mfma_f32_16x16x32_bf16 v[6:9], v[164:167], v[204:207], v[6:9]
	v_mfma_f32_16x16x32_bf16 v[54:57], v[168:171], v[184:187], v[54:57]
	v_mfma_f32_16x16x32_bf16 v[50:53], v[176:179], v[184:187], v[50:53]
	v_mfma_f32_16x16x32_bf16 v[34:37], v[176:179], v[192:195], v[34:37]
	v_mfma_f32_16x16x32_bf16 v[38:41], v[168:171], v[192:195], v[38:41]
	v_mfma_f32_16x16x32_bf16 v[22:25], v[168:171], v[200:203], v[22:25]
	v_mfma_f32_16x16x32_bf16 v[18:21], v[176:179], v[200:203], v[18:21]
	v_mfma_f32_16x16x32_bf16 v[2:5], v[176:179], v[208:211], v[2:5]
	v_mfma_f32_16x16x32_bf16 v[6:9], v[168:171], v[208:211], v[6:9]
	s_setprio 0
	s_barrier
	s_add_u32 vcc_lo, vcc_lo, 0x100
	s_addc_u32 vcc_hi, vcc_hi, 0
	s_cmp_ge_u32 s9, s28
	s_mov_b64 s[38:39], s[60:61]
	s_mov_b32 s26, s9
	s_cbranch_scc0 .LBB0_1000
	s_and_b64 vcc, exec, s[22:23]
	s_cbranch_vccz .LBB0_1003

.LBB0_1054:
	s_add_i32 s96, s26, 2
	s_add_u32 s36, s24, 0x100
	s_addc_u32 s37, s25, 0
	s_add_i32 s9, 0, 0x10000
	s_cmp_eq_u32 s93, s26
	s_cselect_b32 s39, s15, s37
	s_cselect_b32 s38, s14, s36
	v_add_u32_e32 v148, s9, v177
	s_cselect_b32 s27, s23, s95
	s_cselect_b32 s26, s22, s94
	s_add_i32 s78, 0, 0x14000
	ds_read_b128 v[140:143], v148
	ds_read_b128 v[144:147], v148 offset:1024
	ds_read_b128 v[156:159], v148 offset:2048
	ds_read_b128 v[160:163], v148 offset:3072
	v_add_u32_e32 v148, s78, v177
	ds_read_b128 v[164:167], v148
	ds_read_b128 v[168:171], v148 offset:1024
	ds_read_b128 v[172:175], v148 offset:2048
	ds_read_b128 v[180:183], v148 offset:3072
	v_lshl_add_u64 v[148:149], s[24:25], 0, v[136:137]
	s_add_i32 m0, s29, 0xc000
	ds_read_b128 v[184:187], v179
	ds_read_b128 v[188:191], v179 offset:1024
	ds_read_b128 v[192:195], v179 offset:2048
	ds_read_b128 v[196:199], v179 offset:3072
	ds_read_b128 v[200:203], v179 offset:4096
	ds_read_b128 v[204:207], v179 offset:5120
	ds_read_b128 v[208:211], v179 offset:6144
	ds_read_b128 v[212:215], v179 offset:7168
	global_load_lds_dwordx4 v[148:149], off
	s_add_i32 m0, s29, 0xe000
	v_lshl_add_u64 v[148:149], s[24:25], 0, v[138:139]
	global_load_lds_dwordx4 v[148:149], off
	s_waitcnt vmcnt(8)
	s_waitcnt lgkmcnt(0)
	s_barrier
	s_setprio 1
	v_mfma_f32_16x16x32_bf16 v[126:129], v[140:143], v[184:187], v[126:129]
	v_mfma_f32_16x16x32_bf16 v[122:125], v[156:159], v[184:187], v[122:125]
	v_mfma_f32_16x16x32_bf16 v[106:109], v[156:159], v[192:195], v[106:109]
	v_mfma_f32_16x16x32_bf16 v[110:113], v[140:143], v[192:195], v[110:113]
	v_mfma_f32_16x16x32_bf16 v[94:97], v[140:143], v[200:203], v[94:97]
	v_mfma_f32_16x16x32_bf16 v[90:93], v[156:159], v[200:203], v[90:93]
	v_mfma_f32_16x16x32_bf16 v[74:77], v[156:159], v[208:211], v[74:77]
	v_mfma_f32_16x16x32_bf16 v[78:81], v[140:143], v[208:211], v[78:81]
	v_mfma_f32_16x16x32_bf16 v[126:129], v[144:147], v[188:191], v[126:129]
	v_mfma_f32_16x16x32_bf16 v[122:125], v[160:163], v[188:191], v[122:125]
	v_mfma_f32_16x16x32_bf16 v[106:109], v[160:163], v[196:199], v[106:109]
	v_mfma_f32_16x16x32_bf16 v[110:113], v[144:147], v[196:199], v[110:113]
	v_mfma_f32_16x16x32_bf16 v[94:97], v[144:147], v[204:207], v[94:97]
	v_mfma_f32_16x16x32_bf16 v[90:93], v[160:163], v[204:207], v[90:93]
	v_mfma_f32_16x16x32_bf16 v[74:77], v[160:163], v[212:215], v[74:77]
	v_mfma_f32_16x16x32_bf16 v[78:81], v[144:147], v[212:215], v[78:81]
	v_mfma_f32_16x16x32_bf16 v[118:121], v[164:167], v[184:187], v[118:121]
	v_mfma_f32_16x16x32_bf16 v[114:117], v[172:175], v[184:187], v[114:117]
	v_mfma_f32_16x16x32_bf16 v[98:101], v[172:175], v[192:195], v[98:101]
	v_mfma_f32_16x16x32_bf16 v[102:105], v[164:167], v[192:195], v[102:105]
	v_mfma_f32_16x16x32_bf16 v[86:89], v[164:167], v[200:203], v[86:89]
	v_mfma_f32_16x16x32_bf16 v[82:85], v[172:175], v[200:203], v[82:85]
	v_mfma_f32_16x16x32_bf16 v[66:69], v[172:175], v[208:211], v[66:69]
	v_mfma_f32_16x16x32_bf16 v[70:73], v[164:167], v[208:211], v[70:73]
	v_mfma_f32_16x16x32_bf16 v[118:121], v[168:171], v[188:191], v[118:121]
	v_mfma_f32_16x16x32_bf16 v[114:117], v[180:183], v[188:191], v[114:117]
	v_mfma_f32_16x16x32_bf16 v[98:101], v[180:183], v[196:199], v[98:101]
	v_mfma_f32_16x16x32_bf16 v[102:105], v[168:171], v[196:199], v[102:105]
	v_mfma_f32_16x16x32_bf16 v[86:89], v[168:171], v[204:207], v[86:89]
	v_mfma_f32_16x16x32_bf16 v[82:85], v[180:183], v[204:207], v[82:85]
	v_mfma_f32_16x16x32_bf16 v[66:69], v[180:183], v[212:215], v[66:69]
	v_mfma_f32_16x16x32_bf16 v[70:73], v[168:171], v[212:215], v[70:73]
	s_setprio 0
	s_barrier
	s_add_i32 s9, s9, s28
	v_lshl_add_u64 v[148:149], s[26:27], 0, v[0:1]
	s_mov_b32 m0, s9
	ds_read_b128 v[184:187], v179 offset:16384
	ds_read_b128 v[188:191], v179 offset:17408
	ds_read_b128 v[192:195], v179 offset:18432
	ds_read_b128 v[196:199], v179 offset:19456
	ds_read_b128 v[200:203], v179 offset:20480
	ds_read_b128 v[204:207], v179 offset:21504
	ds_read_b128 v[208:211], v179 offset:22528
	ds_read_b128 v[212:215], v179 offset:23552
	global_load_lds_dwordx4 v[148:149], off
	s_add_i32 m0, s9, 0x2000
	s_add_u32 s24, s26, 0xb0000
	v_lshl_add_u64 v[150:151], s[26:27], 0, v[134:135]
	s_addc_u32 s25, s27, 0
	s_add_i32 s9, s78, s28
	global_load_lds_dwordx4 v[150:151], off
	v_lshl_add_u64 v[216:217], s[24:25], 0, v[0:1]
	s_mov_b32 m0, s9
	v_lshl_add_u64 v[218:219], s[38:39], 0, v[132:133]
	global_load_lds_dwordx4 v[216:217], off
	s_add_i32 m0, s9, 0x2000
	v_lshl_add_u64 v[216:217], s[24:25], 0, v[134:135]
	global_load_lds_dwordx4 v[216:217], off
	s_mov_b32 m0, s29
	v_lshl_add_u64 v[216:217], s[38:39], 0, v[130:131]
	global_load_lds_dwordx4 v[216:217], off
	s_mov_b32 m0, s49
	s_nop 0
	global_load_lds_dwordx4 v[218:219], off
	s_waitcnt vmcnt(8)
	s_waitcnt lgkmcnt(0)
	s_barrier
	s_setprio 1
	v_mfma_f32_16x16x32_bf16 v[62:65], v[140:143], v[184:187], v[62:65]
	v_mfma_f32_16x16x32_bf16 v[58:61], v[156:159], v[184:187], v[58:61]
	v_mfma_f32_16x16x32_bf16 v[42:45], v[156:159], v[192:195], v[42:45]
	v_mfma_f32_16x16x32_bf16 v[46:49], v[140:143], v[192:195], v[46:49]
	v_mfma_f32_16x16x32_bf16 v[30:33], v[140:143], v[200:203], v[30:33]
	v_mfma_f32_16x16x32_bf16 v[26:29], v[156:159], v[200:203], v[26:29]
	v_mfma_f32_16x16x32_bf16 v[10:13], v[156:159], v[208:211], v[10:13]
	v_mfma_f32_16x16x32_bf16 v[14:17], v[140:143], v[208:211], v[14:17]
	v_mfma_f32_16x16x32_bf16 v[62:65], v[144:147], v[188:191], v[62:65]
	v_mfma_f32_16x16x32_bf16 v[58:61], v[160:163], v[188:191], v[58:61]
	v_mfma_f32_16x16x32_bf16 v[42:45], v[160:163], v[196:199], v[42:45]
	v_mfma_f32_16x16x32_bf16 v[46:49], v[144:147], v[196:199], v[46:49]
	v_mfma_f32_16x16x32_bf16 v[30:33], v[144:147], v[204:207], v[30:33]
	v_mfma_f32_16x16x32_bf16 v[26:29], v[160:163], v[204:207], v[26:29]
	v_mfma_f32_16x16x32_bf16 v[10:13], v[160:163], v[212:215], v[10:13]
	v_mfma_f32_16x16x32_bf16 v[14:17], v[144:147], v[212:215], v[14:17]
	v_mfma_f32_16x16x32_bf16 v[54:57], v[164:167], v[184:187], v[54:57]
	v_mfma_f32_16x16x32_bf16 v[50:53], v[172:175], v[184:187], v[50:53]
	v_mfma_f32_16x16x32_bf16 v[34:37], v[172:175], v[192:195], v[34:37]
	v_mfma_f32_16x16x32_bf16 v[38:41], v[164:167], v[192:195], v[38:41]
	v_mfma_f32_16x16x32_bf16 v[22:25], v[164:167], v[200:203], v[22:25]
	v_mfma_f32_16x16x32_bf16 v[18:21], v[172:175], v[200:203], v[18:21]
	v_mfma_f32_16x16x32_bf16 v[2:5], v[172:175], v[208:211], v[2:5]
	v_mfma_f32_16x16x32_bf16 v[6:9], v[164:167], v[208:211], v[6:9]
	v_mfma_f32_16x16x32_bf16 v[54:57], v[168:171], v[188:191], v[54:57]
	v_mfma_f32_16x16x32_bf16 v[50:53], v[180:183], v[188:191], v[50:53]
	v_mfma_f32_16x16x32_bf16 v[34:37], v[180:183], v[196:199], v[34:37]
	v_mfma_f32_16x16x32_bf16 v[38:41], v[168:171], v[196:199], v[38:41]
	v_mfma_f32_16x16x32_bf16 v[22:25], v[168:171], v[204:207], v[22:25]
	v_mfma_f32_16x16x32_bf16 v[18:21], v[180:183], v[204:207], v[18:21]
	v_mfma_f32_16x16x32_bf16 v[2:5], v[180:183], v[212:215], v[2:5]
	v_mfma_f32_16x16x32_bf16 v[6:9], v[168:171], v[212:215], v[6:9]
	s_setprio 0
	s_barrier
	s_add_i32 s9, 0, 0x18000
	s_add_i32 s78, 0, 0x1c000
	v_add_u32_e32 v160, s9, v177
	v_add_u32_e32 v180, s78, v177
	ds_read_b128 v[140:143], v160
	ds_read_b128 v[144:147], v160 offset:1024
	ds_read_b128 v[156:159], v160 offset:2048
	ds_read_b128 v[160:163], v160 offset:3072
	ds_read_b128 v[164:167], v180
	ds_read_b128 v[168:171], v180 offset:1024
	ds_read_b128 v[172:175], v180 offset:2048
	ds_read_b128 v[180:183], v180 offset:3072
	s_add_u32 s24, s38, 0xb0000
	s_addc_u32 s25, s39, 0
	s_mov_b32 m0, s50
	v_lshl_add_u64 v[220:221], s[24:25], 0, v[130:131]
	ds_read_b128 v[184:187], v179 offset:32768
	ds_read_b128 v[188:191], v179 offset:33792
	ds_read_b128 v[192:195], v179 offset:34816
	ds_read_b128 v[196:199], v179 offset:35840
	ds_read_b128 v[200:203], v179 offset:36864
	ds_read_b128 v[204:207], v179 offset:37888
	ds_read_b128 v[208:211], v179 offset:38912
	ds_read_b128 v[212:215], v179 offset:39936
	global_load_lds_dwordx4 v[220:221], off
	s_mov_b32 m0, s51
	v_lshl_add_u64 v[220:221], s[24:25], 0, v[132:133]
	global_load_lds_dwordx4 v[220:221], off
	s_waitcnt vmcnt(8)
	s_waitcnt lgkmcnt(0)
	s_barrier
	s_setprio 1
	v_mfma_f32_16x16x32_bf16 v[126:129], v[140:143], v[184:187], v[126:129]
	v_mfma_f32_16x16x32_bf16 v[122:125], v[156:159], v[184:187], v[122:125]
	v_mfma_f32_16x16x32_bf16 v[106:109], v[156:159], v[192:195], v[106:109]
	v_mfma_f32_16x16x32_bf16 v[110:113], v[140:143], v[192:195], v[110:113]
	v_mfma_f32_16x16x32_bf16 v[94:97], v[140:143], v[200:203], v[94:97]
	v_mfma_f32_16x16x32_bf16 v[90:93], v[156:159], v[200:203], v[90:93]
	v_mfma_f32_16x16x32_bf16 v[74:77], v[156:159], v[208:211], v[74:77]
	v_mfma_f32_16x16x32_bf16 v[78:81], v[140:143], v[208:211], v[78:81]
	v_mfma_f32_16x16x32_bf16 v[126:129], v[144:147], v[188:191], v[126:129]
	v_mfma_f32_16x16x32_bf16 v[122:125], v[160:163], v[188:191], v[122:125]
	v_mfma_f32_16x16x32_bf16 v[106:109], v[160:163], v[196:199], v[106:109]
	v_mfma_f32_16x16x32_bf16 v[110:113], v[144:147], v[196:199], v[110:113]
	v_mfma_f32_16x16x32_bf16 v[94:97], v[144:147], v[204:207], v[94:97]
	v_mfma_f32_16x16x32_bf16 v[90:93], v[160:163], v[204:207], v[90:93]
	v_mfma_f32_16x16x32_bf16 v[74:77], v[160:163], v[212:215], v[74:77]
	v_mfma_f32_16x16x32_bf16 v[78:81], v[144:147], v[212:215], v[78:81]
	v_mfma_f32_16x16x32_bf16 v[118:121], v[164:167], v[184:187], v[118:121]
	v_mfma_f32_16x16x32_bf16 v[114:117], v[172:175], v[184:187], v[114:117]
	v_mfma_f32_16x16x32_bf16 v[98:101], v[172:175], v[192:195], v[98:101]
	v_mfma_f32_16x16x32_bf16 v[102:105], v[164:167], v[192:195], v[102:105]
	v_mfma_f32_16x16x32_bf16 v[86:89], v[164:167], v[200:203], v[86:89]
	v_mfma_f32_16x16x32_bf16 v[82:85], v[172:175], v[200:203], v[82:85]
	v_mfma_f32_16x16x32_bf16 v[66:69], v[172:175], v[208:211], v[66:69]
	v_mfma_f32_16x16x32_bf16 v[70:73], v[164:167], v[208:211], v[70:73]
	v_mfma_f32_16x16x32_bf16 v[118:121], v[168:171], v[188:191], v[118:121]
	v_mfma_f32_16x16x32_bf16 v[114:117], v[180:183], v[188:191], v[114:117]
	v_mfma_f32_16x16x32_bf16 v[98:101], v[180:183], v[196:199], v[98:101]
	v_mfma_f32_16x16x32_bf16 v[102:105], v[168:171], v[196:199], v[102:105]
	v_mfma_f32_16x16x32_bf16 v[86:89], v[168:171], v[204:207], v[86:89]
	v_mfma_f32_16x16x32_bf16 v[82:85], v[180:183], v[204:207], v[82:85]
	v_mfma_f32_16x16x32_bf16 v[66:69], v[180:183], v[212:215], v[66:69]
	v_mfma_f32_16x16x32_bf16 v[70:73], v[168:171], v[212:215], v[70:73]
	s_setprio 0
	s_barrier
	s_add_i32 s9, s9, s28
	v_lshl_add_u64 v[148:149], v[148:149], 0, s[70:71]
	s_mov_b32 m0, s9
	ds_read_b128 v[184:187], v179 offset:49152
	ds_read_b128 v[188:191], v179 offset:50176
	ds_read_b128 v[192:195], v179 offset:51200
	ds_read_b128 v[196:199], v179 offset:52224
	ds_read_b128 v[200:203], v179 offset:53248
	ds_read_b128 v[204:207], v179 offset:54272
	ds_read_b128 v[208:211], v179 offset:55296
	ds_read_b128 v[212:215], v179 offset:56320
	global_load_lds_dwordx4 v[148:149], off
	s_add_i32 m0, s9, 0x2000
	s_add_u32 s24, s26, 0xb0080
	v_lshl_add_u64 v[148:149], v[150:151], 0, s[70:71]
	s_addc_u32 s25, s27, 0
	s_add_i32 s9, s78, s28
	global_load_lds_dwordx4 v[148:149], off
	s_mov_b32 m0, s9
	v_lshl_add_u64 v[148:149], s[24:25], 0, v[0:1]
	global_load_lds_dwordx4 v[148:149], off
	s_add_i32 m0, s9, 0x2000
	v_lshl_add_u64 v[148:149], s[24:25], 0, v[134:135]
	global_load_lds_dwordx4 v[148:149], off
	s_mov_b32 m0, s52
	v_lshl_add_u64 v[148:149], v[216:217], 0, s[70:71]
	global_load_lds_dwordx4 v[148:149], off
	s_mov_b32 m0, s53
	v_lshl_add_u64 v[148:149], v[218:219], 0, s[70:71]
	global_load_lds_dwordx4 v[148:149], off
	s_waitcnt vmcnt(8)
	s_waitcnt lgkmcnt(0)
	s_barrier
	s_setprio 1
	v_mfma_f32_16x16x32_bf16 v[62:65], v[140:143], v[184:187], v[62:65]
	v_mfma_f32_16x16x32_bf16 v[58:61], v[156:159], v[184:187], v[58:61]
	v_mfma_f32_16x16x32_bf16 v[42:45], v[156:159], v[192:195], v[42:45]
	v_mfma_f32_16x16x32_bf16 v[46:49], v[140:143], v[192:195], v[46:49]
	v_mfma_f32_16x16x32_bf16 v[30:33], v[140:143], v[200:203], v[30:33]
	v_mfma_f32_16x16x32_bf16 v[26:29], v[156:159], v[200:203], v[26:29]
	v_mfma_f32_16x16x32_bf16 v[10:13], v[156:159], v[208:211], v[10:13]
	v_mfma_f32_16x16x32_bf16 v[14:17], v[140:143], v[208:211], v[14:17]
	v_mfma_f32_16x16x32_bf16 v[62:65], v[144:147], v[188:191], v[62:65]
	v_mfma_f32_16x16x32_bf16 v[58:61], v[160:163], v[188:191], v[58:61]
	v_mfma_f32_16x16x32_bf16 v[42:45], v[160:163], v[196:199], v[42:45]
	v_mfma_f32_16x16x32_bf16 v[46:49], v[144:147], v[196:199], v[46:49]
	v_mfma_f32_16x16x32_bf16 v[30:33], v[144:147], v[204:207], v[30:33]
	v_mfma_f32_16x16x32_bf16 v[26:29], v[160:163], v[204:207], v[26:29]
	v_mfma_f32_16x16x32_bf16 v[10:13], v[160:163], v[212:215], v[10:13]
	v_mfma_f32_16x16x32_bf16 v[14:17], v[144:147], v[212:215], v[14:17]
	v_mfma_f32_16x16x32_bf16 v[54:57], v[164:167], v[184:187], v[54:57]
	v_mfma_f32_16x16x32_bf16 v[50:53], v[172:175], v[184:187], v[50:53]
	v_mfma_f32_16x16x32_bf16 v[34:37], v[172:175], v[192:195], v[34:37]
	v_mfma_f32_16x16x32_bf16 v[38:41], v[164:167], v[192:195], v[38:41]
	v_mfma_f32_16x16x32_bf16 v[22:25], v[164:167], v[200:203], v[22:25]
	v_mfma_f32_16x16x32_bf16 v[18:21], v[172:175], v[200:203], v[18:21]
	v_mfma_f32_16x16x32_bf16 v[2:5], v[172:175], v[208:211], v[2:5]
	v_mfma_f32_16x16x32_bf16 v[6:9], v[164:167], v[208:211], v[6:9]
	v_mfma_f32_16x16x32_bf16 v[54:57], v[168:171], v[188:191], v[54:57]
	v_mfma_f32_16x16x32_bf16 v[50:53], v[180:183], v[188:191], v[50:53]
	v_mfma_f32_16x16x32_bf16 v[34:37], v[180:183], v[196:199], v[34:37]
	v_mfma_f32_16x16x32_bf16 v[38:41], v[168:171], v[196:199], v[38:41]
	v_mfma_f32_16x16x32_bf16 v[22:25], v[168:171], v[204:207], v[22:25]
	v_mfma_f32_16x16x32_bf16 v[18:21], v[180:183], v[204:207], v[18:21]
	v_mfma_f32_16x16x32_bf16 v[2:5], v[180:183], v[212:215], v[2:5]
	v_mfma_f32_16x16x32_bf16 v[6:9], v[168:171], v[212:215], v[6:9]
	s_setprio 0
	s_barrier
	s_add_u32 s94, s94, 0x100
	s_addc_u32 s95, s95, 0
	s_cmp_ge_u32 s96, s92
	s_mov_b64 s[24:25], s[36:37]
	s_mov_b32 s26, s96
	s_cbranch_scc0 .LBB0_1054
	s_and_b64 vcc, exec, s[12:13]
	s_cbranch_vccz .LBB0_1057
